# tmi with FFN-out operands in a half-split tile-major layout ([k-tile][32-col half][row][64B]): each LDS-DMA instruction reads 1 KB fully contiguous
# speedup vs baseline: 1.0046x; 1.0046x over previous
; __device__ __forceinline__ unsigned cvt_pk_bf16(float lo, float hi) { const pk_f2_t v = {lo, hi}; return __builtin_bit_cast(unsigned, __builtin_convertvector(v, pk_bf2_t)); }
; #define GAS __attribute__((address_space(1)))
;     if (ldk == 0) ldk = K;
;     const int nblk = (N + 63) / 64, kb = item / nblk, nb = item % nblk, k0 = 64 * kb, n0 = 64 * nb;
;     const bool ok = n0 + lane < N;
;     float tv[64];
;     { const GAS float* wp = (const GAS float*)(W + (size_t)k0 * N + n0 + (ok ? lane : 0));
; #pragma unroll
;       for (int i = 0; i < 64; ++i) tv[i] = wp[(size_t)i * N]; }
; #pragma unroll
;     for (int j = 0; j < 32; ++j) scr[j * 65 + lane] = pg8::cvt_pk_bf16(tv[2 * j], tv[2 * j + 1]);
; __device__ __forceinline__ void p0_prologue(Frame& F, const Args& a) {
;     ...
;         if (r < 2 * I_FI) { const int f = r / I_FI; p0_transpose_item64(a.in[5] + ((size_t)l * 2 + f) * D * 2 * FF, D, 2 * FF, (bf16*)(ws + WS_WFI + ((size_t)l * 2 + f) * SZ_WFI1), MapFfnIn(), scu, r % I_FI, F.lane); continue; } r -= 2 * I_FI;
;         if (r < 2 * I_FO) { const int f = r / I_FO; p0_transpose_item64(a.in[6] + ((size_t)l * 2 + f) * FF * D, FF, D, (bf16*)(ws + WS_WFO + ((size_t)l * 2 + f) * SZ_WFO1), MapIdent(), scu, r % I_FO, F.lane); continue; } r -= 2 * I_FO;
.LBB0_108:
	s_andn2_b64 vcc, exec, s[4:5]
	s_cbranch_vccnz .LBB0_110
	s_add_i32 s1, s31, 0xffffd400
	s_cmpk_gt_u32 s1, 0xaff
	s_cselect_b64 s[4:5], -1, 0
	v_cndmask_b32_e64 v2, 0, 1, s[4:5]
	s_lshl_b32 s26, s0, 1
	v_readfirstlane_b32 s4, v2
	s_or_b32 s4, s26, s4
	s_mul_i32 s26, s4, 0x2c00000
	s_mul_hi_i32 s5, s4, 0x2c00000
	s_add_u32 s27, s18, s26
	s_addc_u32 s28, s19, s5
	s_mul_hi_i32 s5, s4, 0x1600000
	s_mul_i32 s4, s4, 0x1600000
	s_add_u32 s4, s43, s4
	s_addc_u32 s5, s44, s5
	s_add_i32 s26, s31, 0xffffc900
	s_cmpk_lt_u32 s1, 0xb00
	s_cselect_b32 s1, s1, s26
	s_lshl_b32 s26, s1, 1
	s_and_b32 s26, s26, 0x1fc0
	s_lshl_b32 s1, s1, 6
	s_and_b32 s1, s1, 0x7c0
	s_lshl_b32 s29, s26, 13
	s_add_u32 s27, s27, s29
	s_addc_u32 s29, s28, 0
	s_lshl_b32 s28, s1, 2
	s_add_u32 s28, s27, s28
	s_addc_u32 s29, s29, 0
	v_mov_b32_e32 v15, v13
	v_lshl_add_u64 v[2:3], s[28:29], 0, v[14:15]
	s_movk_i32 s27, 0x2000
	v_add_co_u32_e32 v6, vcc, s27, v2
	s_movk_i32 s27, 0x4000
	s_nop 0
	v_addc_co_u32_e32 v7, vcc, 0, v3, vcc
	global_load_dword v5, v[6:7], off
	v_add_co_u32_e32 v6, vcc, s27, v2
	s_movk_i32 s27, 0x6000
	s_nop 0
	v_addc_co_u32_e32 v7, vcc, 0, v3, vcc
	v_add_co_u32_e32 v8, vcc, s27, v2
	global_load_dword v6, v[6:7], off
	s_nop 0
	v_addc_co_u32_e32 v9, vcc, 0, v3, vcc
	global_load_dword v7, v[8:9], off
	v_add_co_u32_e32 v8, vcc, s50, v2
	s_mov_b32 s27, 0xa000
	s_nop 0
	v_addc_co_u32_e32 v9, vcc, 0, v3, vcc
	v_add_co_u32_e32 v16, vcc, s27, v2
	s_mov_b32 s27, 0xc000
	s_nop 0
	v_addc_co_u32_e32 v17, vcc, 0, v3, vcc
	global_load_dword v8, v[8:9], off
	s_lshl_b32 s26, s26, 9
	s_lshr_b32 s100, s1, 8
	s_mul_i32 s100, s100, 0x2c0000
	s_add_u32 s26, s26, s100
	global_load_dword v9, v[16:17], off
	v_add_co_u32_e32 v16, vcc, s27, v2
	s_mov_b32 s27, 0xe000
	s_nop 0
	v_addc_co_u32_e32 v17, vcc, 0, v3, vcc
	global_load_dword v15, v[16:17], off
	v_add_co_u32_e32 v16, vcc, s27, v2
	s_mov_b32 s27, 0x12000
	s_nop 0
	v_addc_co_u32_e32 v17, vcc, 0, v3, vcc
	v_add_co_u32_e32 v38, vcc, s54, v2
	global_load_dword v16, v[16:17], off
	s_nop 0
	v_addc_co_u32_e32 v39, vcc, 0, v3, vcc
	global_load_dword v17, v[38:39], off
	v_add_co_u32_e32 v38, vcc, s27, v2
	s_mov_b32 s27, 0x14000
	s_nop 0
	v_addc_co_u32_e32 v39, vcc, 0, v3, vcc
	v_add_co_u32_e32 v40, vcc, s27, v2
	global_load_dword v38, v[38:39], off
	s_nop 0
	v_addc_co_u32_e32 v41, vcc, 0, v3, vcc
	global_load_dword v39, v[40:41], off
	v_add_co_u32_e32 v40, vcc, s57, v2
	s_mov_b32 s27, 0x18000
	s_nop 0
	v_addc_co_u32_e32 v41, vcc, 0, v3, vcc
	v_add_co_u32_e32 v42, vcc, s27, v2
	s_mov_b32 s27, 0x1a000
	s_nop 0
	v_addc_co_u32_e32 v43, vcc, 0, v3, vcc
	global_load_dword v40, v[40:41], off
	s_add_u32 s4, s4, s26
	global_load_dword v41, v[42:43], off
	v_add_co_u32_e32 v42, vcc, s27, v2
	s_mov_b32 s27, 0x1c000
	s_nop 0
	v_addc_co_u32_e32 v43, vcc, 0, v3, vcc
	v_add_co_u32_e32 v44, vcc, s27, v2
	s_mov_b32 s27, 0x1e000
	s_nop 0
	v_addc_co_u32_e32 v45, vcc, 0, v3, vcc
	global_load_dword v42, v[42:43], off
	s_addc_u32 s5, s5, 0
	global_load_dword v43, v[44:45], off
	v_add_co_u32_e32 v44, vcc, s27, v2
	global_load_dword v4, v14, s[28:29]
	s_nop 0
	v_addc_co_u32_e32 v45, vcc, 0, v3, vcc
	v_add_co_u32_e32 v46, vcc, s62, v2
	global_load_dword v44, v[44:45], off
	s_nop 0
	v_addc_co_u32_e32 v47, vcc, 0, v3, vcc
	global_load_dword v45, v[46:47], off
	v_add_co_u32_e32 v46, vcc, s63, v2
	s_nop 1
	v_addc_co_u32_e32 v47, vcc, 0, v3, vcc
	v_add_co_u32_e32 v48, vcc, s64, v2
	global_load_dword v46, v[46:47], off
	s_nop 0
	v_addc_co_u32_e32 v49, vcc, 0, v3, vcc
	global_load_dword v47, v[48:49], off
	v_add_co_u32_e32 v48, vcc, s65, v2
	s_nop 1
	v_addc_co_u32_e32 v49, vcc, 0, v3, vcc
	global_load_dword v50, v[48:49], off
	v_add_co_u32_e32 v48, vcc, s66, v2
	s_nop 1
	v_addc_co_u32_e32 v49, vcc, 0, v3, vcc
	global_load_dword v51, v[48:49], off
	v_add_co_u32_e32 v48, vcc, s67, v2
	s_nop 1
	v_addc_co_u32_e32 v49, vcc, 0, v3, vcc
	global_load_dword v52, v[48:49], off
	v_add_co_u32_e32 v48, vcc, s68, v2
	s_nop 1
	v_addc_co_u32_e32 v49, vcc, 0, v3, vcc
	global_load_dword v53, v[48:49], off
	v_add_co_u32_e32 v48, vcc, s69, v2
	s_nop 1
	v_addc_co_u32_e32 v49, vcc, 0, v3, vcc
	global_load_dword v54, v[48:49], off
	v_add_co_u32_e32 v48, vcc, s70, v2
	s_nop 1
	v_addc_co_u32_e32 v49, vcc, 0, v3, vcc
	global_load_dword v55, v[48:49], off
	v_add_co_u32_e32 v48, vcc, s71, v2
	s_nop 1
	v_addc_co_u32_e32 v49, vcc, 0, v3, vcc
	global_load_dword v56, v[48:49], off
	v_add_co_u32_e32 v48, vcc, s72, v2
	s_nop 1
	v_addc_co_u32_e32 v49, vcc, 0, v3, vcc
	global_load_dword v57, v[48:49], off
	v_add_co_u32_e32 v48, vcc, s73, v2
	s_nop 1
	v_addc_co_u32_e32 v49, vcc, 0, v3, vcc
	global_load_dword v58, v[48:49], off
	v_add_co_u32_e32 v48, vcc, s74, v2
	s_nop 1
	v_addc_co_u32_e32 v49, vcc, 0, v3, vcc
	global_load_dword v59, v[48:49], off
	v_add_co_u32_e32 v48, vcc, s75, v2
	s_nop 1
	v_addc_co_u32_e32 v49, vcc, 0, v3, vcc
	global_load_dword v60, v[48:49], off
	v_add_co_u32_e32 v48, vcc, s76, v2
	s_nop 1
	v_addc_co_u32_e32 v49, vcc, 0, v3, vcc
	global_load_dword v61, v[48:49], off
	v_add_co_u32_e32 v48, vcc, s77, v2
	s_nop 1
	v_addc_co_u32_e32 v49, vcc, 0, v3, vcc
	global_load_dword v62, v[48:49], off
	v_add_co_u32_e32 v48, vcc, s78, v2
	s_nop 1
	v_addc_co_u32_e32 v49, vcc, 0, v3, vcc
	global_load_dword v63, v[48:49], off
	v_add_co_u32_e32 v48, vcc, s79, v2
	s_nop 1
	v_addc_co_u32_e32 v49, vcc, 0, v3, vcc
	global_load_dword v64, v[48:49], off
	v_add_co_u32_e32 v48, vcc, s81, v2
	s_nop 1
	v_addc_co_u32_e32 v49, vcc, 0, v3, vcc
	global_load_dword v65, v[48:49], off
	v_add_co_u32_e32 v48, vcc, s61, v2
	s_nop 1
	v_addc_co_u32_e32 v49, vcc, 0, v3, vcc
	global_load_dword v66, v[48:49], off
; __device__ __forceinline__ unsigned cvt_pk_bf16(float lo, float hi) { const pk_f2_t v = {lo, hi}; return __builtin_bit_cast(unsigned, __builtin_convertvector(v, pk_bf2_t)); }
; #define GAS __attribute__((address_space(1)))
;     ...
;     { const GAS float* wp = (const GAS float*)(W + (size_t)k0 * N + n0 + (ok ? lane : 0));
; #pragma unroll
;       for (int i = 0; i < 64; ++i) tv[i] = wp[(size_t)i * N]; }
; #pragma unroll
;     for (int j = 0; j < 32; ++j) scr[j * 65 + lane] = pg8::cvt_pk_bf16(tv[2 * j], tv[2 * j + 1]);
	v_add_co_u32_e32 v48, vcc, s82, v2
	s_nop 1
	v_addc_co_u32_e32 v49, vcc, 0, v3, vcc
	global_load_dword v67, v[48:49], off
	v_add_co_u32_e32 v48, vcc, s83, v2
	s_nop 1
	v_addc_co_u32_e32 v49, vcc, 0, v3, vcc
	global_load_dword v68, v[48:49], off
	v_add_co_u32_e32 v48, vcc, s84, v2
	s_nop 1
	v_addc_co_u32_e32 v49, vcc, 0, v3, vcc
	global_load_dword v69, v[48:49], off
	v_add_co_u32_e32 v48, vcc, s85, v2
	s_nop 1
	v_addc_co_u32_e32 v49, vcc, 0, v3, vcc
	global_load_dword v70, v[48:49], off
	v_add_co_u32_e32 v48, vcc, s86, v2
	s_nop 1
	v_addc_co_u32_e32 v49, vcc, 0, v3, vcc
	global_load_dword v71, v[48:49], off
	v_add_co_u32_e32 v48, vcc, s87, v2
	s_nop 1
	v_addc_co_u32_e32 v49, vcc, 0, v3, vcc
	global_load_dword v72, v[48:49], off
	v_add_co_u32_e32 v48, vcc, s88, v2
	s_nop 1
	v_addc_co_u32_e32 v49, vcc, 0, v3, vcc
	global_load_dword v73, v[48:49], off
	v_add_co_u32_e32 v48, vcc, s89, v2
	s_nop 1
	v_addc_co_u32_e32 v49, vcc, 0, v3, vcc
	global_load_dword v74, v[48:49], off
	v_add_co_u32_e32 v48, vcc, s90, v2
	s_nop 1
	v_addc_co_u32_e32 v49, vcc, 0, v3, vcc
	global_load_dword v75, v[48:49], off
	v_add_co_u32_e32 v48, vcc, s91, v2
	s_nop 1
	v_addc_co_u32_e32 v49, vcc, 0, v3, vcc
	global_load_dword v76, v[48:49], off
	v_add_co_u32_e32 v48, vcc, s92, v2
	s_nop 1
	v_addc_co_u32_e32 v49, vcc, 0, v3, vcc
	global_load_dword v77, v[48:49], off
	v_add_co_u32_e32 v48, vcc, s93, v2
	s_nop 1
	v_addc_co_u32_e32 v49, vcc, 0, v3, vcc
	global_load_dword v78, v[48:49], off
	v_add_co_u32_e32 v48, vcc, s94, v2
	s_nop 1
	v_addc_co_u32_e32 v49, vcc, 0, v3, vcc
	global_load_dword v79, v[48:49], off
	v_add_co_u32_e32 v48, vcc, s95, v2
	s_nop 1
	v_addc_co_u32_e32 v49, vcc, 0, v3, vcc
	global_load_dword v80, v[48:49], off
	v_add_co_u32_e32 v48, vcc, s96, v2
	s_nop 1
	v_addc_co_u32_e32 v49, vcc, 0, v3, vcc
	global_load_dword v81, v[48:49], off
	v_add_co_u32_e32 v48, vcc, s97, v2
	s_nop 1
	v_addc_co_u32_e32 v49, vcc, 0, v3, vcc
	global_load_dword v83, v[48:49], off
	v_add_co_u32_e32 v48, vcc, s24, v2
	s_nop 1
	v_addc_co_u32_e32 v49, vcc, 0, v3, vcc
	global_load_dword v84, v[48:49], off
	v_add_co_u32_e32 v48, vcc, s25, v2
	s_nop 1
	v_addc_co_u32_e32 v49, vcc, 0, v3, vcc
	global_load_dword v85, v[48:49], off
	v_add_co_u32_e32 v48, vcc, s37, v2
	s_nop 1
	v_addc_co_u32_e32 v49, vcc, 0, v3, vcc
	global_load_dword v86, v[48:49], off
	v_add_co_u32_e32 v48, vcc, s38, v2
	s_nop 1
	v_addc_co_u32_e32 v49, vcc, 0, v3, vcc
	global_load_dword v87, v[48:49], off
	v_add_co_u32_e32 v48, vcc, s39, v2
	s_nop 1
	v_addc_co_u32_e32 v49, vcc, 0, v3, vcc
	global_load_dword v88, v[48:49], off
	v_add_co_u32_e32 v48, vcc, s40, v2
	s_nop 1
	v_addc_co_u32_e32 v49, vcc, 0, v3, vcc
	global_load_dword v89, v[48:49], off
	v_add_co_u32_e32 v48, vcc, s22, v2
	s_nop 1
	v_addc_co_u32_e32 v49, vcc, 0, v3, vcc
	global_load_dword v90, v[48:49], off
	v_add_co_u32_e32 v48, vcc, s23, v2
	s_nop 1
	v_addc_co_u32_e32 v49, vcc, 0, v3, vcc
	global_load_dword v91, v[48:49], off
	v_add_co_u32_e32 v48, vcc, s41, v2
	s_nop 1
	v_addc_co_u32_e32 v49, vcc, 0, v3, vcc
	global_load_dword v92, v[48:49], off
	v_add_co_u32_e32 v48, vcc, s42, v2
	s_nop 1
	v_addc_co_u32_e32 v49, vcc, 0, v3, vcc
	global_load_dword v93, v[48:49], off
	v_add_co_u32_e32 v48, vcc, s33, v2
	s_nop 1
	v_addc_co_u32_e32 v49, vcc, 0, v3, vcc
	v_add_co_u32_e32 v2, vcc, s47, v2
	global_load_dword v48, v[48:49], off
	s_nop 0
	v_addc_co_u32_e32 v3, vcc, 0, v3, vcc
	global_load_dword v2, v[2:3], off
	s_waitcnt vmcnt(49)
	v_cvt_pk_bf16_f32 v3, v4, v5
	v_cvt_pk_bf16_f32 v4, v6, v7
	ds_write2_b32 v22, v3, v4 offset1:65
	v_cvt_pk_bf16_f32 v3, v8, v9
	v_cvt_pk_bf16_f32 v4, v15, v16
	ds_write2_b32 v22, v3, v4 offset0:130 offset1:195
	v_cvt_pk_bf16_f32 v3, v17, v38
	v_cvt_pk_bf16_f32 v4, v39, v40
	ds_write2_b32 v28, v3, v4 offset0:4 offset1:69
	v_cvt_pk_bf16_f32 v3, v41, v42
	s_waitcnt vmcnt(48)
	v_cvt_pk_bf16_f32 v4, v43, v44
	ds_write2_b32 v28, v3, v4 offset0:134 offset1:199
	s_waitcnt vmcnt(46)
	v_cvt_pk_bf16_f32 v3, v45, v46
	s_waitcnt vmcnt(44)
	v_cvt_pk_bf16_f32 v4, v47, v50
	ds_write2_b32 v29, v3, v4 offset0:8 offset1:73
	s_waitcnt vmcnt(42)
	v_cvt_pk_bf16_f32 v3, v51, v52
	s_waitcnt vmcnt(40)
	v_cvt_pk_bf16_f32 v4, v53, v54
	ds_write2_b32 v29, v3, v4 offset0:138 offset1:203
	s_waitcnt vmcnt(38)
	v_cvt_pk_bf16_f32 v3, v55, v56
	s_waitcnt vmcnt(36)
	v_cvt_pk_bf16_f32 v4, v57, v58
	ds_write2_b32 v30, v3, v4 offset0:12 offset1:77
	s_waitcnt vmcnt(34)
	v_cvt_pk_bf16_f32 v3, v59, v60
	s_waitcnt vmcnt(32)
	v_cvt_pk_bf16_f32 v4, v61, v62
	ds_write2_b32 v30, v3, v4 offset0:142 offset1:207
	s_waitcnt vmcnt(30)
	v_cvt_pk_bf16_f32 v3, v63, v64
	s_waitcnt vmcnt(28)
; __device__ __forceinline__ unsigned cvt_pk_bf16(float lo, float hi) { const pk_f2_t v = {lo, hi}; return __builtin_bit_cast(unsigned, __builtin_convertvector(v, pk_bf2_t)); }
; #define GAS __attribute__((address_space(1)))
; #define LAS __attribute__((address_space(3)))
; #define LDS_WAIT() asm volatile("s_waitcnt lgkmcnt(0)" ::: "memory")
;     ...
;     for (int j = 0; j < 32; ++j) scr[j * 65 + lane] = pg8::cvt_pk_bf16(tv[2 * j], tv[2 * j + 1]);
;     LDS_WAIT(); asm volatile("" ::: "memory");
;     const int c = lane & 7;
; #pragma unroll
;     for (int jj = 0; jj < 8; ++jj) { const int n = (lane >> 3) + 8 * jj; const LAS unsigned* q = scr + (4 * c) * 65 + n;
;         v4u o; o.x = q[0]; o.y = q[65]; o.z = q[130]; o.w = q[195];
;         if (n0 + n < N) *(GAS v4u*)(WT + (size_t)mp(n0 + n) * ldk + koff + k0 + 8 * c) = o; }
	v_cvt_pk_bf16_f32 v4, v65, v66
	ds_write2_b32 v31, v3, v4 offset0:16 offset1:81
	s_waitcnt vmcnt(26)
	v_cvt_pk_bf16_f32 v3, v67, v68
	s_waitcnt vmcnt(24)
	v_cvt_pk_bf16_f32 v4, v69, v70
	ds_write2_b32 v31, v3, v4 offset0:146 offset1:211
	s_waitcnt vmcnt(22)
	v_cvt_pk_bf16_f32 v3, v71, v72
	s_waitcnt vmcnt(20)
	v_cvt_pk_bf16_f32 v4, v73, v74
	ds_write2_b32 v32, v3, v4 offset0:20 offset1:85
	s_waitcnt vmcnt(18)
	v_cvt_pk_bf16_f32 v3, v75, v76
	s_waitcnt vmcnt(16)
	v_cvt_pk_bf16_f32 v4, v77, v78
	ds_write2_b32 v32, v3, v4 offset0:150 offset1:215
	s_waitcnt vmcnt(14)
	v_cvt_pk_bf16_f32 v3, v79, v80
	s_waitcnt vmcnt(12)
	v_cvt_pk_bf16_f32 v4, v81, v83
	ds_write2_b32 v33, v3, v4 offset0:24 offset1:89
	s_waitcnt vmcnt(10)
	v_cvt_pk_bf16_f32 v3, v84, v85
	s_waitcnt vmcnt(8)
	v_cvt_pk_bf16_f32 v4, v86, v87
	ds_write2_b32 v33, v3, v4 offset0:154 offset1:219
	v_or_b32_e32 v15, s1, v11
	v_and_b32_e32 v200, 63, v12
	v_bfe_u32 v201, v12, 6, 1
	v_lshl_or_b32 v200, v201, 14, v200
	v_mov_b32_e32 v201, 0
	v_lshl_add_u64 v[16:17], s[4:5], 0, v[200:201]
	s_waitcnt vmcnt(6)
	v_cvt_pk_bf16_f32 v3, v88, v89
	v_and_b32_e32 v42, 0xff, v15
	v_lshlrev_b32_e32 v42, 6, v42
	v_mov_b32_e32 v43, v13
	v_lshl_add_u64 v[42:43], v[16:17], 0, v[42:43]
	v_or_b32_e32 v15, s1, v19
	s_waitcnt vmcnt(4)
	v_cvt_pk_bf16_f32 v4, v90, v91
	ds_write2_b32 v34, v3, v4 offset0:28 offset1:93
	s_waitcnt vmcnt(2)
	v_cvt_pk_bf16_f32 v3, v92, v93
	s_waitcnt vmcnt(0)
	v_cvt_pk_bf16_f32 v2, v48, v2
	ds_write2_b32 v34, v3, v2 offset0:158 offset1:223
	s_waitcnt lgkmcnt(0)
	ds_read2_b32 v[2:3], v23 offset0:65 offset1:73
	ds_read2_b32 v[38:39], v23 offset0:130 offset1:138
	ds_read2_b32 v[4:5], v23 offset0:195 offset1:203
	ds_read2_b32 v[40:41], v23 offset1:8
	s_waitcnt lgkmcnt(3)
	v_mov_b32_e32 v7, v2
	s_waitcnt lgkmcnt(2)
	v_mov_b32_e32 v8, v38
	s_waitcnt lgkmcnt(1)
	v_mov_b32_e32 v9, v4
	s_waitcnt lgkmcnt(0)
	v_mov_b32_e32 v6, v40
	global_store_dwordx4 v[42:43], v[6:9], off
	v_mov_b32_e32 v2, v41
	v_mov_b32_e32 v4, v39
	v_or_b32_e32 v6, s1, v18
	v_and_b32_e32 v6, 0xff, v6
	v_lshlrev_b32_e32 v6, 6, v6
	v_mov_b32_e32 v7, v13
	v_lshl_add_u64 v[6:7], v[16:17], 0, v[6:7]
	global_store_dwordx4 v[6:7], v[2:5], off
	ds_read2_b32 v[38:39], v23 offset0:16 offset1:24
	ds_read2_b32 v[2:3], v23 offset0:81 offset1:89
	ds_read2_b32 v[40:41], v23 offset0:146 offset1:154
	ds_read2_b32 v[4:5], v23 offset0:211 offset1:219
	v_and_b32_e32 v42, 0xff, v15
	v_lshlrev_b32_e32 v42, 6, v42
	v_mov_b32_e32 v43, v13
	s_waitcnt lgkmcnt(3)
	v_mov_b32_e32 v6, v38
	s_waitcnt lgkmcnt(2)
	v_mov_b32_e32 v7, v2
	s_waitcnt lgkmcnt(1)
	v_mov_b32_e32 v8, v40
	s_waitcnt lgkmcnt(0)
	v_mov_b32_e32 v9, v4
	v_lshl_add_u64 v[42:43], v[16:17], 0, v[42:43]
	global_store_dwordx4 v[42:43], v[6:9], off
	v_mov_b32_e32 v2, v39
	v_mov_b32_e32 v4, v41
	v_or_b32_e32 v6, s1, v20
	v_and_b32_e32 v6, 0xff, v6
	v_lshlrev_b32_e32 v6, 6, v6
	v_mov_b32_e32 v7, v13
	v_lshl_add_u64 v[6:7], v[16:17], 0, v[6:7]
	global_store_dwordx4 v[6:7], v[2:5], off
	ds_read2_b32 v[38:39], v23 offset0:32 offset1:40
	ds_read2_b32 v[2:3], v23 offset0:97 offset1:105
	ds_read2_b32 v[40:41], v23 offset0:162 offset1:170
	ds_read2_b32 v[4:5], v23 offset0:227 offset1:235
	v_or_b32_e32 v15, s1, v24
	v_and_b32_e32 v42, 0xff, v15
	v_lshlrev_b32_e32 v42, 6, v42
	v_mov_b32_e32 v43, v13
	s_waitcnt lgkmcnt(3)
	v_mov_b32_e32 v6, v38
	s_waitcnt lgkmcnt(2)
	v_mov_b32_e32 v7, v2
	s_waitcnt lgkmcnt(1)
	v_mov_b32_e32 v8, v40
	s_waitcnt lgkmcnt(0)
	v_mov_b32_e32 v9, v4
	v_lshl_add_u64 v[42:43], v[16:17], 0, v[42:43]
	global_store_dwordx4 v[42:43], v[6:9], off
	v_mov_b32_e32 v2, v39
	v_mov_b32_e32 v4, v41
	v_or_b32_e32 v6, s1, v25
	v_and_b32_e32 v6, 0xff, v6
	v_lshlrev_b32_e32 v6, 6, v6
	v_mov_b32_e32 v7, v13
	v_lshl_add_u64 v[6:7], v[16:17], 0, v[6:7]
	global_store_dwordx4 v[6:7], v[2:5], off
	ds_read2_b32 v[38:39], v23 offset0:48 offset1:56
	ds_read2_b32 v[2:3], v23 offset0:113 offset1:121
	ds_read2_b32 v[40:41], v23 offset0:178 offset1:186
	ds_read2_b32 v[4:5], v23 offset0:243 offset1:251
	v_or_b32_e32 v15, s1, v26
	v_and_b32_e32 v42, 0xff, v15
	v_lshlrev_b32_e32 v42, 6, v42
	v_mov_b32_e32 v43, v13
	s_waitcnt lgkmcnt(3)
	v_mov_b32_e32 v6, v38
	s_waitcnt lgkmcnt(2)
	v_mov_b32_e32 v7, v2
	s_waitcnt lgkmcnt(1)
	v_mov_b32_e32 v8, v40
	s_waitcnt lgkmcnt(0)
	v_mov_b32_e32 v9, v4
	v_lshl_add_u64 v[42:43], v[16:17], 0, v[42:43]
	global_store_dwordx4 v[42:43], v[6:9], off
	v_mov_b32_e32 v2, v39
	v_mov_b32_e32 v4, v41
	v_or_b32_e32 v6, s1, v27
	v_and_b32_e32 v6, 0xff, v6
	v_lshlrev_b32_e32 v6, 6, v6
	v_mov_b32_e32 v7, v13
	v_lshl_add_u64 v[6:7], v[16:17], 0, v[6:7]
	global_store_dwordx4 v[6:7], v[2:5], off
	s_waitcnt lgkmcnt(0)

; __device__ __forceinline__ unsigned cvt_pk_bf16(float lo, float hi) { const pk_f2_t v = {lo, hi}; return __builtin_bit_cast(unsigned, __builtin_convertvector(v, pk_bf2_t)); }
; __device__ __forceinline__ float silu_f(float g) { return g * __builtin_amdgcn_rcpf(1.0f + __builtin_amdgcn_exp2f(-1.4426950408889634f * g)); }
;     __device__ __forceinline__ void operator()(const pg8::f32x4 (&acc)[2][2][4][2], const pg8::Unit& u, int wr, int wc, int fr, int fq) const {
;         const int row0 = u.pm * 256 + wr * 64 + fr, col0 = u.pn * 128 + wc * 32 + 8 * fq;
;         bf16* base = O + (size_t)row0 * FF + col0;
; #pragma unroll
;         for (int ai = 0; ai < 2; ++ai)
; #pragma unroll
;             for (int m = 0; m < 4; ++m) {
;                 pg8::u32x4 w;
;                 { const pg8::f32x4 g = acc[ai][0][m][0], uu = acc[ai][1][m][0];
;                   w.x = pg8::cvt_pk_bf16(silu_f(g[0]) * uu[0], silu_f(g[1]) * uu[1]); w.y = pg8::cvt_pk_bf16(silu_f(g[2]) * uu[2], silu_f(g[3]) * uu[3]); }
;                 { const pg8::f32x4 g = acc[ai][0][m][1], uu = acc[ai][1][m][1];
;                   w.z = pg8::cvt_pk_bf16(silu_f(g[0]) * uu[0], silu_f(g[1]) * uu[1]); w.w = pg8::cvt_pk_bf16(silu_f(g[2]) * uu[2], silu_f(g[3]) * uu[3]); }
;                 *(pg8::u32x4*)(base + (size_t)(ai * 128 + m * 16) * FF) = w;
;                 asm volatile("" ::: "memory");
;             }
.LBB0_282:
	s_lshl_b32 s100, s26, 1
	v_lshrrev_b32_e32 v141, 6, v144
	v_add_u32_e32 v141, s100, v141
	v_lshlrev_b32_e32 v141, 15, v141
	v_bfe_u32 v140, v144, 5, 1
	v_lshl_or_b32 v141, v140, 14, v141
	v_and_b32_e32 v140, 31, v144
	v_lshlrev_b32_e32 v140, 1, v140
	v_lshl_add_u32 v140, v142, 6, v140
	v_add_u32_e32 v140, v140, v141
	s_mul_i32 s100, s27, 0x2c0000
	s_add_u32 s100, s6, s100
	s_addc_u32 s101, s7, 0
	v_mov_b32_e32 v141, 0
	v_lshl_add_u64 v[140:141], s[100:101], 0, v[140:141]
	s_mov_b64 s[18:19], -1
	v_mul_f32_e32 v150, 0xbfb8aa3b, v126
	v_mul_f32_e32 v151, 0xbfb8aa3b, v127
	v_mul_f32_e32 v152, 0xbfb8aa3b, v128
	v_mul_f32_e32 v153, 0xbfb8aa3b, v129
	v_mul_f32_e32 v154, 0xbfb8aa3b, v118
	v_mul_f32_e32 v155, 0xbfb8aa3b, v119
	v_mul_f32_e32 v156, 0xbfb8aa3b, v120
	v_mul_f32_e32 v157, 0xbfb8aa3b, v121
	v_exp_f32_e32 v150, v150
	v_exp_f32_e32 v151, v151
	v_exp_f32_e32 v152, v152
	v_exp_f32_e32 v153, v153
	v_exp_f32_e32 v154, v154
	v_exp_f32_e32 v155, v155
	v_exp_f32_e32 v156, v156
	v_exp_f32_e32 v157, v157
	v_add_f32_e32 v150, 1.0, v150
	v_add_f32_e32 v151, 1.0, v151
	v_add_f32_e32 v152, 1.0, v152
	v_add_f32_e32 v153, 1.0, v153
	v_add_f32_e32 v154, 1.0, v154
	v_add_f32_e32 v155, 1.0, v155
	v_add_f32_e32 v156, 1.0, v156
	v_add_f32_e32 v157, 1.0, v157
	v_rcp_f32_e32 v150, v150
	v_rcp_f32_e32 v151, v151
	v_rcp_f32_e32 v152, v152
	v_rcp_f32_e32 v153, v153
	v_rcp_f32_e32 v154, v154
	v_rcp_f32_e32 v155, v155
	v_rcp_f32_e32 v156, v156
	v_rcp_f32_e32 v157, v157
	v_mul_f32_e32 v150, v126, v150
	v_mul_f32_e32 v151, v127, v151
	v_mul_f32_e32 v152, v128, v152
	v_mul_f32_e32 v153, v129, v153
	v_mul_f32_e32 v154, v118, v154
	v_mul_f32_e32 v155, v119, v155
	v_mul_f32_e32 v156, v120, v156
	v_mul_f32_e32 v157, v121, v157
	v_mul_f32_e32 v122, v150, v122
	v_mul_f32_e32 v123, v151, v123
	v_mul_f32_e32 v124, v152, v124
	v_mul_f32_e32 v125, v153, v125
	v_mul_f32_e32 v114, v154, v114
	v_mul_f32_e32 v115, v155, v115
	v_mul_f32_e32 v116, v156, v116
	v_mul_f32_e32 v117, v157, v117
	v_cvt_pk_bf16_f32 v122, v122, v123
	v_cvt_pk_bf16_f32 v123, v124, v125
	v_cvt_pk_bf16_f32 v124, v114, v115
	v_cvt_pk_bf16_f32 v125, v116, v117
	flat_store_dwordx4 v[140:141], v[122:125]
	v_mul_f32_e32 v158, 0xbfb8aa3b, v110
	v_mul_f32_e32 v159, 0xbfb8aa3b, v111
	v_mul_f32_e32 v160, 0xbfb8aa3b, v112
	v_mul_f32_e32 v161, 0xbfb8aa3b, v113
	v_mul_f32_e32 v162, 0xbfb8aa3b, v102
	v_mul_f32_e32 v163, 0xbfb8aa3b, v103
	v_mul_f32_e32 v164, 0xbfb8aa3b, v104
	v_mul_f32_e32 v165, 0xbfb8aa3b, v105
	v_exp_f32_e32 v158, v158
	v_exp_f32_e32 v159, v159
	v_exp_f32_e32 v160, v160
	v_exp_f32_e32 v161, v161
	v_exp_f32_e32 v162, v162
	v_exp_f32_e32 v163, v163
	v_exp_f32_e32 v164, v164
	v_exp_f32_e32 v165, v165
	v_add_co_u32_e32 v166, vcc, 0x400, v140
	v_add_f32_e32 v158, 1.0, v158
	v_add_f32_e32 v159, 1.0, v159
	v_add_f32_e32 v160, 1.0, v160
	v_add_f32_e32 v161, 1.0, v161
	v_add_f32_e32 v162, 1.0, v162
	v_add_f32_e32 v163, 1.0, v163
	v_add_f32_e32 v164, 1.0, v164
	v_add_f32_e32 v165, 1.0, v165
	v_addc_co_u32_e32 v167, vcc, 0, v141, vcc
	v_rcp_f32_e32 v158, v158
	v_rcp_f32_e32 v159, v159
	v_rcp_f32_e32 v160, v160
	v_rcp_f32_e32 v161, v161
	v_rcp_f32_e32 v162, v162
	v_rcp_f32_e32 v163, v163
	v_rcp_f32_e32 v164, v164
	v_rcp_f32_e32 v165, v165
	v_mul_f32_e32 v158, v110, v158
	v_mul_f32_e32 v159, v111, v159
	v_mul_f32_e32 v160, v112, v160
	v_mul_f32_e32 v161, v113, v161
	v_mul_f32_e32 v162, v102, v162
	v_mul_f32_e32 v163, v103, v163
	v_mul_f32_e32 v164, v104, v164
	v_mul_f32_e32 v165, v105, v165
	v_mul_f32_e32 v106, v158, v106
	v_mul_f32_e32 v107, v159, v107
	v_mul_f32_e32 v108, v160, v108
	v_mul_f32_e32 v109, v161, v109
	v_mul_f32_e32 v98, v162, v98
	v_mul_f32_e32 v99, v163, v99
	v_mul_f32_e32 v100, v164, v100
	v_mul_f32_e32 v101, v165, v101
	v_cvt_pk_bf16_f32 v106, v106, v107
	v_cvt_pk_bf16_f32 v107, v108, v109
	v_cvt_pk_bf16_f32 v108, v98, v99
	v_cvt_pk_bf16_f32 v109, v100, v101
	flat_store_dwordx4 v[166:167], v[106:109]
	v_mul_f32_e32 v150, 0xbfb8aa3b, v94
	v_mul_f32_e32 v151, 0xbfb8aa3b, v95
	v_mul_f32_e32 v152, 0xbfb8aa3b, v96
	v_mul_f32_e32 v153, 0xbfb8aa3b, v97
	v_mul_f32_e32 v154, 0xbfb8aa3b, v86
	v_mul_f32_e32 v155, 0xbfb8aa3b, v87
	v_mul_f32_e32 v156, 0xbfb8aa3b, v88
	v_mul_f32_e32 v157, 0xbfb8aa3b, v89
	v_exp_f32_e32 v150, v150
	v_exp_f32_e32 v151, v151
	v_exp_f32_e32 v152, v152
	v_exp_f32_e32 v153, v153
	v_exp_f32_e32 v154, v154
	v_exp_f32_e32 v155, v155
	v_exp_f32_e32 v156, v156
	v_exp_f32_e32 v157, v157
	v_add_co_u32_e32 v148, vcc, 0x800, v140
	v_add_f32_e32 v150, 1.0, v150
	v_add_f32_e32 v151, 1.0, v151
	v_add_f32_e32 v152, 1.0, v152
	v_add_f32_e32 v153, 1.0, v153
	v_add_f32_e32 v154, 1.0, v154
	v_add_f32_e32 v155, 1.0, v155
	v_add_f32_e32 v156, 1.0, v156
	v_add_f32_e32 v157, 1.0, v157
	v_addc_co_u32_e32 v149, vcc, 0, v141, vcc
	v_rcp_f32_e32 v150, v150
	v_rcp_f32_e32 v151, v151
	v_rcp_f32_e32 v152, v152
	v_rcp_f32_e32 v153, v153
	v_rcp_f32_e32 v154, v154
	v_rcp_f32_e32 v155, v155
	v_rcp_f32_e32 v156, v156
	v_rcp_f32_e32 v157, v157
	v_mul_f32_e32 v150, v94, v150
	v_mul_f32_e32 v151, v95, v151
	v_mul_f32_e32 v152, v96, v152
	v_mul_f32_e32 v153, v97, v153
	v_mul_f32_e32 v154, v86, v154
	v_mul_f32_e32 v155, v87, v155
	v_mul_f32_e32 v156, v88, v156
	v_mul_f32_e32 v157, v89, v157
	v_mul_f32_e32 v90, v150, v90
	v_mul_f32_e32 v91, v151, v91
	v_mul_f32_e32 v92, v152, v92
	v_mul_f32_e32 v93, v153, v93
	v_mul_f32_e32 v82, v154, v82
	v_mul_f32_e32 v83, v155, v83
	v_mul_f32_e32 v84, v156, v84
	v_mul_f32_e32 v85, v157, v85
	v_cvt_pk_bf16_f32 v90, v90, v91
	v_cvt_pk_bf16_f32 v91, v92, v93
	v_cvt_pk_bf16_f32 v92, v82, v83
	v_cvt_pk_bf16_f32 v93, v84, v85
	flat_store_dwordx4 v[148:149], v[90:93]
; __device__ __forceinline__ unsigned cvt_pk_bf16(float lo, float hi) { const pk_f2_t v = {lo, hi}; return __builtin_bit_cast(unsigned, __builtin_convertvector(v, pk_bf2_t)); }
; __device__ __forceinline__ float silu_f(float g) { return g * __builtin_amdgcn_rcpf(1.0f + __builtin_amdgcn_exp2f(-1.4426950408889634f * g)); }
;     __device__ __forceinline__ void operator()(const pg8::f32x4 (&acc)[2][2][4][2], const pg8::Unit& u, int wr, int wc, int fr, int fq) const {
;     ...
;             for (int m = 0; m < 4; ++m) {
;                 pg8::u32x4 w;
;                 { const pg8::f32x4 g = acc[ai][0][m][0], uu = acc[ai][1][m][0];
;                   w.x = pg8::cvt_pk_bf16(silu_f(g[0]) * uu[0], silu_f(g[1]) * uu[1]); w.y = pg8::cvt_pk_bf16(silu_f(g[2]) * uu[2], silu_f(g[3]) * uu[3]); }
;                 { const pg8::f32x4 g = acc[ai][0][m][1], uu = acc[ai][1][m][1];
;                   w.z = pg8::cvt_pk_bf16(silu_f(g[0]) * uu[0], silu_f(g[1]) * uu[1]); w.w = pg8::cvt_pk_bf16(silu_f(g[2]) * uu[2], silu_f(g[3]) * uu[3]); }
;                 *(pg8::u32x4*)(base + (size_t)(ai * 128 + m * 16) * FF) = w;
	v_mul_f32_e32 v158, 0xbfb8aa3b, v78
	v_mul_f32_e32 v159, 0xbfb8aa3b, v79
	v_mul_f32_e32 v160, 0xbfb8aa3b, v80
	v_mul_f32_e32 v161, 0xbfb8aa3b, v81
	v_mul_f32_e32 v162, 0xbfb8aa3b, v70
	v_mul_f32_e32 v163, 0xbfb8aa3b, v71
	v_mul_f32_e32 v164, 0xbfb8aa3b, v72
	v_mul_f32_e32 v165, 0xbfb8aa3b, v73
	v_exp_f32_e32 v158, v158
	v_exp_f32_e32 v159, v159
	v_exp_f32_e32 v160, v160
	v_exp_f32_e32 v161, v161
	v_exp_f32_e32 v162, v162
	v_exp_f32_e32 v163, v163
	v_exp_f32_e32 v164, v164
	v_exp_f32_e32 v165, v165
	v_add_co_u32_e32 v166, vcc, 0xc00, v140
	v_add_f32_e32 v158, 1.0, v158
	v_add_f32_e32 v159, 1.0, v159
	v_add_f32_e32 v160, 1.0, v160
	v_add_f32_e32 v161, 1.0, v161
	v_add_f32_e32 v162, 1.0, v162
	v_add_f32_e32 v163, 1.0, v163
	v_add_f32_e32 v164, 1.0, v164
	v_add_f32_e32 v165, 1.0, v165
	v_addc_co_u32_e32 v167, vcc, 0, v141, vcc
	v_rcp_f32_e32 v158, v158
	v_rcp_f32_e32 v159, v159
	v_rcp_f32_e32 v160, v160
	v_rcp_f32_e32 v161, v161
	v_rcp_f32_e32 v162, v162
	v_rcp_f32_e32 v163, v163
	v_rcp_f32_e32 v164, v164
	v_rcp_f32_e32 v165, v165
	v_mul_f32_e32 v158, v78, v158
	v_mul_f32_e32 v159, v79, v159
	v_mul_f32_e32 v160, v80, v160
	v_mul_f32_e32 v161, v81, v161
	v_mul_f32_e32 v162, v70, v162
	v_mul_f32_e32 v163, v71, v163
	v_mul_f32_e32 v164, v72, v164
	v_mul_f32_e32 v165, v73, v165
	v_mul_f32_e32 v74, v158, v74
	v_mul_f32_e32 v75, v159, v75
	v_mul_f32_e32 v76, v160, v76
	v_mul_f32_e32 v77, v161, v77
	v_mul_f32_e32 v66, v162, v66
	v_mul_f32_e32 v67, v163, v67
	v_mul_f32_e32 v68, v164, v68
	v_mul_f32_e32 v69, v165, v69
	v_cvt_pk_bf16_f32 v74, v74, v75
	v_cvt_pk_bf16_f32 v75, v76, v77
	v_cvt_pk_bf16_f32 v76, v66, v67
	v_cvt_pk_bf16_f32 v77, v68, v69
	flat_store_dwordx4 v[166:167], v[74:77]
	v_mul_f32_e32 v150, 0xbfb8aa3b, v62
	v_mul_f32_e32 v151, 0xbfb8aa3b, v63
	v_mul_f32_e32 v152, 0xbfb8aa3b, v64
	v_mul_f32_e32 v153, 0xbfb8aa3b, v65
	v_mul_f32_e32 v154, 0xbfb8aa3b, v54
	v_mul_f32_e32 v155, 0xbfb8aa3b, v55
	v_mul_f32_e32 v156, 0xbfb8aa3b, v56
	v_mul_f32_e32 v157, 0xbfb8aa3b, v57
	v_exp_f32_e32 v150, v150
	v_exp_f32_e32 v151, v151
	v_exp_f32_e32 v152, v152
	v_exp_f32_e32 v153, v153
	v_exp_f32_e32 v154, v154
	v_exp_f32_e32 v155, v155
	v_exp_f32_e32 v156, v156
	v_exp_f32_e32 v157, v157
	v_add_co_u32_e32 v148, vcc, 0x2000, v140
	v_add_f32_e32 v150, 1.0, v150
	v_add_f32_e32 v151, 1.0, v151
	v_add_f32_e32 v152, 1.0, v152
	v_add_f32_e32 v153, 1.0, v153
	v_add_f32_e32 v154, 1.0, v154
	v_add_f32_e32 v155, 1.0, v155
	v_add_f32_e32 v156, 1.0, v156
	v_add_f32_e32 v157, 1.0, v157
	v_addc_co_u32_e32 v149, vcc, 0, v141, vcc
	v_rcp_f32_e32 v150, v150
	v_rcp_f32_e32 v151, v151
	v_rcp_f32_e32 v152, v152
	v_rcp_f32_e32 v153, v153
	v_rcp_f32_e32 v154, v154
	v_rcp_f32_e32 v155, v155
	v_rcp_f32_e32 v156, v156
	v_rcp_f32_e32 v157, v157
	v_mul_f32_e32 v150, v62, v150
	v_mul_f32_e32 v151, v63, v151
	v_mul_f32_e32 v152, v64, v152
	v_mul_f32_e32 v153, v65, v153
	v_mul_f32_e32 v154, v54, v154
	v_mul_f32_e32 v155, v55, v155
	v_mul_f32_e32 v156, v56, v156
	v_mul_f32_e32 v157, v57, v157
	v_mul_f32_e32 v58, v150, v58
	v_mul_f32_e32 v59, v151, v59
	v_mul_f32_e32 v60, v152, v60
	v_mul_f32_e32 v61, v153, v61
	v_mul_f32_e32 v50, v154, v50
	v_mul_f32_e32 v51, v155, v51
	v_mul_f32_e32 v52, v156, v52
	v_mul_f32_e32 v53, v157, v53
	v_cvt_pk_bf16_f32 v58, v58, v59
	v_cvt_pk_bf16_f32 v59, v60, v61
	v_cvt_pk_bf16_f32 v60, v50, v51
	v_cvt_pk_bf16_f32 v61, v52, v53
	flat_store_dwordx4 v[148:149], v[58:61]
	v_mul_f32_e32 v158, 0xbfb8aa3b, v46
	v_mul_f32_e32 v159, 0xbfb8aa3b, v47
	v_mul_f32_e32 v160, 0xbfb8aa3b, v48
	v_mul_f32_e32 v161, 0xbfb8aa3b, v49
	v_mul_f32_e32 v162, 0xbfb8aa3b, v38
	v_mul_f32_e32 v163, 0xbfb8aa3b, v39
	v_mul_f32_e32 v164, 0xbfb8aa3b, v40
	v_mul_f32_e32 v165, 0xbfb8aa3b, v41
	v_exp_f32_e32 v158, v158
	v_exp_f32_e32 v159, v159
	v_exp_f32_e32 v160, v160
	v_exp_f32_e32 v161, v161
	v_exp_f32_e32 v162, v162
	v_exp_f32_e32 v163, v163
	v_exp_f32_e32 v164, v164
	v_exp_f32_e32 v165, v165
	v_add_co_u32_e32 v166, vcc, 0x2400, v140
	v_add_f32_e32 v158, 1.0, v158
	v_add_f32_e32 v159, 1.0, v159
	v_add_f32_e32 v160, 1.0, v160
	v_add_f32_e32 v161, 1.0, v161
	v_add_f32_e32 v162, 1.0, v162
	v_add_f32_e32 v163, 1.0, v163
	v_add_f32_e32 v164, 1.0, v164
	v_add_f32_e32 v165, 1.0, v165
	v_addc_co_u32_e32 v167, vcc, 0, v141, vcc
	v_rcp_f32_e32 v158, v158
	v_rcp_f32_e32 v159, v159
	v_rcp_f32_e32 v160, v160
; __device__ __forceinline__ unsigned cvt_pk_bf16(float lo, float hi) { const pk_f2_t v = {lo, hi}; return __builtin_bit_cast(unsigned, __builtin_convertvector(v, pk_bf2_t)); }
; __device__ __forceinline__ float silu_f(float g) { return g * __builtin_amdgcn_rcpf(1.0f + __builtin_amdgcn_exp2f(-1.4426950408889634f * g)); }
;     __device__ __forceinline__ void operator()(const pg8::f32x4 (&acc)[2][2][4][2], const pg8::Unit& u, int wr, int wc, int fr, int fq) const {
;     ...
;             for (int m = 0; m < 4; ++m) {
;                 pg8::u32x4 w;
;                 { const pg8::f32x4 g = acc[ai][0][m][0], uu = acc[ai][1][m][0];
;                   w.x = pg8::cvt_pk_bf16(silu_f(g[0]) * uu[0], silu_f(g[1]) * uu[1]); w.y = pg8::cvt_pk_bf16(silu_f(g[2]) * uu[2], silu_f(g[3]) * uu[3]); }
;                 { const pg8::f32x4 g = acc[ai][0][m][1], uu = acc[ai][1][m][1];
;                   w.z = pg8::cvt_pk_bf16(silu_f(g[0]) * uu[0], silu_f(g[1]) * uu[1]); w.w = pg8::cvt_pk_bf16(silu_f(g[2]) * uu[2], silu_f(g[3]) * uu[3]); }
;                 *(pg8::u32x4*)(base + (size_t)(ai * 128 + m * 16) * FF) = w;
;                 asm volatile("" ::: "memory");
;             }
	v_rcp_f32_e32 v161, v161
	v_rcp_f32_e32 v162, v162
	v_rcp_f32_e32 v163, v163
	v_rcp_f32_e32 v164, v164
	v_rcp_f32_e32 v165, v165
	v_mul_f32_e32 v158, v46, v158
	v_mul_f32_e32 v159, v47, v159
	v_mul_f32_e32 v160, v48, v160
	v_mul_f32_e32 v161, v49, v161
	v_mul_f32_e32 v162, v38, v162
	v_mul_f32_e32 v163, v39, v163
	v_mul_f32_e32 v164, v40, v164
	v_mul_f32_e32 v165, v41, v165
	v_mul_f32_e32 v42, v158, v42
	v_mul_f32_e32 v43, v159, v43
	v_mul_f32_e32 v44, v160, v44
	v_mul_f32_e32 v45, v161, v45
	v_mul_f32_e32 v34, v162, v34
	v_mul_f32_e32 v35, v163, v35
	v_mul_f32_e32 v36, v164, v36
	v_mul_f32_e32 v37, v165, v37
	v_cvt_pk_bf16_f32 v42, v42, v43
	v_cvt_pk_bf16_f32 v43, v44, v45
	v_cvt_pk_bf16_f32 v44, v34, v35
	v_cvt_pk_bf16_f32 v45, v36, v37
	flat_store_dwordx4 v[166:167], v[42:45]
	v_mul_f32_e32 v150, 0xbfb8aa3b, v30
	v_mul_f32_e32 v151, 0xbfb8aa3b, v31
	v_mul_f32_e32 v152, 0xbfb8aa3b, v32
	v_mul_f32_e32 v153, 0xbfb8aa3b, v33
	v_mul_f32_e32 v154, 0xbfb8aa3b, v22
	v_mul_f32_e32 v155, 0xbfb8aa3b, v23
	v_mul_f32_e32 v156, 0xbfb8aa3b, v24
	v_mul_f32_e32 v157, 0xbfb8aa3b, v25
	v_exp_f32_e32 v150, v150
	v_exp_f32_e32 v151, v151
	v_exp_f32_e32 v152, v152
	v_exp_f32_e32 v153, v153
	v_exp_f32_e32 v154, v154
	v_exp_f32_e32 v155, v155
	v_exp_f32_e32 v156, v156
	v_exp_f32_e32 v157, v157
	v_add_co_u32_e32 v148, vcc, 0x2800, v140
	v_add_f32_e32 v150, 1.0, v150
	v_add_f32_e32 v151, 1.0, v151
	v_add_f32_e32 v152, 1.0, v152
	v_add_f32_e32 v153, 1.0, v153
	v_add_f32_e32 v154, 1.0, v154
	v_add_f32_e32 v155, 1.0, v155
	v_add_f32_e32 v156, 1.0, v156
	v_add_f32_e32 v157, 1.0, v157
	v_addc_co_u32_e32 v149, vcc, 0, v141, vcc
	v_rcp_f32_e32 v150, v150
	v_rcp_f32_e32 v151, v151
	v_rcp_f32_e32 v152, v152
	v_rcp_f32_e32 v153, v153
	v_rcp_f32_e32 v154, v154
	v_rcp_f32_e32 v155, v155
	v_rcp_f32_e32 v156, v156
	v_rcp_f32_e32 v157, v157
	v_mul_f32_e32 v150, v30, v150
	v_mul_f32_e32 v151, v31, v151
	v_mul_f32_e32 v152, v32, v152
	v_mul_f32_e32 v153, v33, v153
	v_mul_f32_e32 v154, v22, v154
	v_mul_f32_e32 v155, v23, v155
	v_mul_f32_e32 v156, v24, v156
	v_mul_f32_e32 v157, v25, v157
	v_mul_f32_e32 v26, v150, v26
	v_mul_f32_e32 v27, v151, v27
	v_mul_f32_e32 v28, v152, v28
	v_mul_f32_e32 v29, v153, v29
	v_mul_f32_e32 v18, v154, v18
	v_mul_f32_e32 v19, v155, v19
	v_mul_f32_e32 v20, v156, v20
	v_mul_f32_e32 v21, v157, v21
	v_cvt_pk_bf16_f32 v26, v26, v27
	v_cvt_pk_bf16_f32 v27, v28, v29
	v_cvt_pk_bf16_f32 v28, v18, v19
	v_cvt_pk_bf16_f32 v29, v20, v21
	flat_store_dwordx4 v[148:149], v[26:29]
	v_mul_f32_e32 v158, 0xbfb8aa3b, v14
	v_mul_f32_e32 v159, 0xbfb8aa3b, v15
	v_mul_f32_e32 v160, 0xbfb8aa3b, v16
	v_mul_f32_e32 v161, 0xbfb8aa3b, v17
	v_mul_f32_e32 v162, 0xbfb8aa3b, v6
	v_mul_f32_e32 v163, 0xbfb8aa3b, v7
	v_mul_f32_e32 v164, 0xbfb8aa3b, v8
	v_mul_f32_e32 v165, 0xbfb8aa3b, v9
	v_exp_f32_e32 v158, v158
	v_exp_f32_e32 v159, v159
	v_exp_f32_e32 v160, v160
	v_exp_f32_e32 v161, v161
	v_exp_f32_e32 v162, v162
	v_exp_f32_e32 v163, v163
	v_exp_f32_e32 v164, v164
	v_exp_f32_e32 v165, v165
	v_add_co_u32_e32 v166, vcc, 0x2c00, v140
	v_add_f32_e32 v158, 1.0, v158
	v_add_f32_e32 v159, 1.0, v159
	v_add_f32_e32 v160, 1.0, v160
	v_add_f32_e32 v161, 1.0, v161
	v_add_f32_e32 v162, 1.0, v162
	v_add_f32_e32 v163, 1.0, v163
	v_add_f32_e32 v164, 1.0, v164
	v_add_f32_e32 v165, 1.0, v165
	v_addc_co_u32_e32 v167, vcc, 0, v141, vcc
	v_rcp_f32_e32 v158, v158
	v_rcp_f32_e32 v159, v159
	v_rcp_f32_e32 v160, v160
	v_rcp_f32_e32 v161, v161
	v_rcp_f32_e32 v162, v162
	v_rcp_f32_e32 v163, v163
	v_rcp_f32_e32 v164, v164
	v_rcp_f32_e32 v165, v165
	v_mul_f32_e32 v158, v14, v158
	v_mul_f32_e32 v159, v15, v159
	v_mul_f32_e32 v160, v16, v160
	v_mul_f32_e32 v161, v17, v161
	v_mul_f32_e32 v162, v6, v162
	v_mul_f32_e32 v163, v7, v163
	v_mul_f32_e32 v164, v8, v164
	v_mul_f32_e32 v165, v9, v165
	v_mul_f32_e32 v10, v158, v10
	v_mul_f32_e32 v11, v159, v11
	v_mul_f32_e32 v12, v160, v12
	v_mul_f32_e32 v13, v161, v13
	v_mul_f32_e32 v2, v162, v2
	v_mul_f32_e32 v3, v163, v3
	v_mul_f32_e32 v4, v164, v4
	v_mul_f32_e32 v5, v165, v5
	v_cvt_pk_bf16_f32 v10, v10, v11
	v_cvt_pk_bf16_f32 v11, v12, v13
	v_cvt_pk_bf16_f32 v12, v2, v3
	v_cvt_pk_bf16_f32 v13, v4, v5
	flat_store_dwordx4 v[166:167], v[10:13]
	s_andn2_b64 vcc, exec, s[38:39]
	s_cbranch_vccnz .LBB0_275
	s_andn2_b64 vcc, exec, s[0:1]
	s_cbranch_vccnz .LBB0_274
	s_barrier
	s_branch .LBB0_274

; template <class Epi, class Sched, bool ALIGN_EPI = false, bool SP2 = false>
; __device__ __forceinline__ void gemm_phase(PG8_LAS unsigned char* lds, const Gemm g, const Sched& S, const Epi& E, int wave_s) {
;     int tid_ = (wave_s << 6) | fresh_lane(); asm volatile("" : "+v"(tid_));
;     const int tid = tid_, wid = __builtin_amdgcn_readfirstlane(tid >> 6), lane = tid & 63, wr = wid >> 2, wc = wid & 3, fr = lane & 15, fq = lane >> 4;
;     const int K = g.K, nt = K / BK;
;     unsigned voffA[2], voffB[2];
; #pragma unroll
;     for (int i = 0; i < 2; ++i) { int R, C; stage_rc(tid * 16 + i * 8192, R, C); const int Rb = Epi::PERM ? ((R & ~31) + perm32(R & 31)) : R;
;         voffA[i] = (unsigned)(R * g.lda + C) * 2u; voffB[i] = (unsigned)(Rb * g.ldb + C) * 2u; }
;     const size_t kstep = (size_t)(BK * 2);
;     const size_t hstepA = (size_t)HALF * g.lda * 2, hstepB = (size_t)HALF * g.ldb * 2;
;     const size_t tstepA = 2 * hstepA, tstepB = 2 * hstepB;
;     const unsigned ldsw = (unsigned)wid * 1024u;
;     const int aoff = lds_byte(wr * 64 + fr, fq * 8), boff = lds_byte(wc * 32 + fr, fq * 8);
;     ...
;     Unit cur, nxt; int ui = 0;
;     if (!S.next(0, cur)) return;
;     f32x4 acc[2][2][4][2];
; #pragma unroll
;     for (int a = 0; a < 2; ++a)
; #pragma unroll
;         for (int b = 0; b < 2; ++b)
; #pragma unroll
;             for (int m = 0; m < 4; ++m)
; #pragma unroll
;                 for (int n = 0; n < 2; ++n) acc[a][b][m][n] = (f32x4){0.f, 0.f, 0.f, 0.f};
;     bf16x8 At[4][2], B0[2][2], B1[2][2];
;     const char* cA = (const char*)g.A + (size_t)cur.pm * tstepA; const char* cB = (const char*)g.Bt + (size_t)cur.pn * tstepB;
;     S.a_ready(cur);
;     if constexpr (SP2) {
;         PG8_STAGE(PG8_SB(0, 0), cB, voffB); PG8_STAGE(PG8_SB(0, 1), cB + hstepB, voffB); PG8_STAGE(PG8_SA(0, 0), cA, voffA); PG8_STAGE(PG8_SA(0, 1), cA + hstepA, voffA);
;         if (wr == 1) PG8_BAR;
;         PG8_WAIT_V(2); PG8_BAR;
;         PG8_STAGE(PG8_SB(1, 0), cB + kstep, voffB); PG8_STAGE(PG8_SA(1, 0), cA + kstep, voffA); PG8_STAGE(PG8_SB(1, 1), cB + hstepB + kstep, voffB);
;         PG8_WAIT_V(6); PG8_BAR;
;     } else {
;         PG8_STAGE(PG8_SB(0, 0), cB, voffB); PG8_STAGE(PG8_SA(0, 0), cA, voffA); PG8_STAGE(PG8_SB(0, 1), cB + hstepB, voffB); PG8_STAGE(PG8_SA(0, 1), cA + hstepA, voffA);
;         if (wr == 1) PG8_BAR;
;         PG8_WAIT_V(4); PG8_BAR;
.LBB0_341:
	v_mov_b32_e32 v0, v1
	s_andn2_b32 s2, s2, 63
	v_mbcnt_lo_u32_b32 v0, -1, v0
	v_mbcnt_hi_u32_b32 v0, -1, v0
	v_readlane_b32 s6, v254, 2
	v_or_b32_e32 v18, s2, v0
	v_readlane_b32 s7, v254, 3
	s_andn2_b64 vcc, exec, s[6:7]
	v_readfirstlane_b32 s12, v18
	s_cbranch_vccnz .LBB0_365
	v_lshlrev_b32_e32 v0, 4, v18
	v_add_u32_e32 v2, 0x2000, v0
	v_ashrrev_i32_e32 v3, 31, v2
	v_lshrrev_b32_e32 v3, 22, v3
	v_add_u32_e32 v3, v2, v3
	v_ashrrev_i32_e32 v10, 10, v3
	v_mul_i32_i24_e32 v3, 0x400, v10
	v_sub_u32_e32 v2, v2, v3
	v_lshrrev_b32_e32 v3, 4, v2
	v_bitop3_b32 v2, v3, v2, 32 bitop3:0x6c
	v_ashrrev_i32_e32 v3, 31, v2
	v_lshrrev_b32_e32 v3, 26, v3
	v_add_u32_e32 v3, v2, v3
	v_ashrrev_i32_e32 v11, 6, v3
	v_lshlrev_b32_e32 v5, 5, v10
	v_and_b32_e32 v3, 0xc0, v3
	v_and_b32_e32 v12, 32, v5
	v_sub_u32_e32 v2, v2, v3
	v_mov_b32_e32 v5, 1
	v_ashrrev_i16_sdwa v2, v5, sext(v2) dst_sel:DWORD dst_unused:UNUSED_PAD src0_sel:DWORD src1_sel:BYTE_0
	v_bfe_i32 v13, v2, 0, 16
	v_bfe_i32 v2, v18, 27, 1
	v_lshrrev_b32_e32 v2, 22, v2
	v_add_u32_e32 v2, v0, v2
	v_and_b32_e32 v2, 0xfffffc00, v2
	v_sub_u32_e32 v0, v0, v2
	s_add_u32 s2, s10, 0x22d90000
	v_lshrrev_b32_e32 v2, 4, v0
	v_ashrrev_i32_e32 v3, 31, v18
	s_addc_u32 s22, s11, 0
	s_mul_i32 s6, s78, 0x2c00000
	v_bitop3_b32 v0, v2, v0, 32 bitop3:0x6c
	v_lshrrev_b32_e32 v3, 26, v3
	s_add_u32 s6, s10, s6
	v_lshlrev_b32_e32 v4, 3, v10
	v_ashrrev_i32_e32 v2, 31, v0
	v_add_u32_e32 v3, v18, v3
	s_addc_u32 s7, s11, 0
	v_and_b32_e32 v4, 0x7ffff0, v4
	v_lshrrev_b32_e32 v2, 26, v2
	v_ashrrev_i32_e32 v15, 6, v3
	s_add_u32 s33, s6, 0xb190000
	v_add_u32_e32 v4, v11, v4
	s_movk_i32 s6, 32
	v_add_u32_e32 v2, v0, v2
	v_lshlrev_b32_e32 v3, 3, v15
	v_lshl_add_u32 v228, v4, 5, v13
	v_lshl_add_u32 v228, v12, 8, v228
	v_lshlrev_b32_e32 v228, 1, v228
	v_mov_b32_e32 v229, 0
	v_mul_lo_u32 v4, v4, s6
	v_ashrrev_i32_e32 v14, 6, v2
	v_and_b32_e32 v3, 0x7ffff0, v3
	s_addc_u32 s36, s7, 0
	s_ashr_i32 s13, s12, 6
	v_lshl_add_u32 v4, v12, 8, v4
	v_add_u32_e32 v3, v14, v3
	v_and_b32_e32 v2, 0xc0, v2
	s_ashr_i32 s14, s12, 8
	s_lshl_b32 s37, s13, 10
	s_waitcnt vmcnt(0)
	v_add_lshl_u32 v130, v4, v13, 1
	v_mov_b32_e32 v226, v3
	v_mul_lo_u32 v3, v3, s6
	v_lshlrev_b32_e32 v4, 5, v15
	v_sub_u32_e32 v0, v0, v2
	v_readlane_b32 s6, v255, 22
	v_and_b32_e32 v16, 32, v4
	v_ashrrev_i16_sdwa v0, v5, sext(v0) dst_sel:DWORD dst_unused:UNUSED_PAD src0_sel:DWORD src1_sel:BYTE_0
	s_add_u32 s18, s33, s6
	v_readlane_b32 s6, v255, 20
	v_lshl_add_u32 v3, v16, 8, v3
	v_bfe_i32 v17, v0, 0, 16
	s_addc_u32 s19, s36, s6
	s_add_i32 s42, s37, 0
	v_add_lshl_u32 v0, v3, v17, 1
	v_lshl_add_u32 v226, v226, 5, v17
	v_lshl_add_u32 v226, v16, 8, v226
	v_lshlrev_b32_e32 v226, 1, v226
	v_mov_b32_e32 v227, 0
	s_add_i32 m0, s42, 0x10000
	v_mov_b32_e32 v131, v1
	global_load_lds_dwordx4 v0, s[18:19]
	s_add_i32 m0, s42, 0x12000
	s_add_u32 s6, s18, 0x2000
	global_load_lds_dwordx4 v130, s[18:19]
	s_addc_u32 s7, s19, 0
	s_add_i32 m0, s42, 0x14000
	v_lshl_add_u64 v[8:9], s[18:19], 0, v[0:1]
	global_load_lds_dwordx4 v0, s[6:7]
	s_add_i32 m0, s42, 0x16000
	v_lshl_add_u64 v[6:7], s[18:19], 0, v[130:131]
	global_load_lds_dwordx4 v130, s[6:7]
	v_readlane_b32 s6, v255, 19
	s_add_u32 s16, s2, s6
	v_readlane_b32 s6, v255, 16
	s_addc_u32 s17, s22, s6
	s_add_i32 s43, s42, 0x2000
	s_mov_b32 m0, s42
	s_add_u32 s6, s16, 0x2000
	global_load_lds_dwordx4 v226, s[16:17]
	s_mov_b32 m0, s43
	s_addc_u32 s7, s17, 0
	s_add_i32 s44, s42, 0x4000
	global_load_lds_dwordx4 v228, s[16:17]
	s_mov_b32 m0, s44
	s_add_i32 s45, s42, 0x6000
	global_load_lds_dwordx4 v226, s[6:7]
	s_mov_b32 m0, s45
	s_cmp_eq_u32 s14, 1
	global_load_lds_dwordx4 v228, s[6:7]
	v_lshl_add_u64 v[2:3], s[16:17], 0, v[226:227]
	s_cselect_b64 s[6:7], -1, 0
	s_cmp_lg_u32 s14, 1
	v_lshl_add_u64 v[4:5], s[16:17], 0, v[228:229]
	s_cbranch_scc1 .LBB0_344
	s_barrier
.LBB0_344:
	s_add_u32 s8, s10, 0x16d90000
	s_addc_u32 s9, s11, 0
	s_mul_i32 s15, s78, 0x48000
	s_add_u32 s10, s10, s15
	s_addc_u32 s11, s11, 0
	v_bfe_u32 v19, v18, 4, 2
	s_add_u32 s46, s10, 0x104000
	v_and_b32_e32 v20, 15, v18
	v_lshlrev_b32_e32 v21, 4, v19
	v_lshlrev_b32_e32 v18, 2, v18
	s_addc_u32 s47, s11, 0
	v_lshl_or_b32 v158, s14, 6, v20
	v_lshl_or_b32 v20, v20, 6, v21
	s_lshl_b32 s10, s14, 13
	v_and_b32_e32 v18, 32, v18
	v_bitop3_b32 v21, v20, s10, v18 bitop3:0xde
	s_lshl_b32 s10, s13, 5
	s_and_b32 s13, s10, 0x60
	s_add_i32 m0, s42, 0x18000
	s_mov_b64 s[100:101], 0x8000
	v_lshl_add_u64 v[8:9], v[8:9], 0, s[100:101]
	s_lshl_b32 s10, s13, 7
	s_waitcnt vmcnt(2)
	s_barrier
	global_load_lds_dwordx4 v[8:9], off
	v_lshl_add_u64 v[6:7], v[6:7], 0, s[100:101]
	s_add_i32 m0, s42, 0x1a000
	s_add_i32 s48, s42, 0x8000
	s_add_i32 s49, s42, 0xa000
	v_bitop3_b32 v159, v20, s10, v18 bitop3:0xde
	global_load_lds_dwordx4 v[6:7], off
	s_mov_b64 s[100:101], 0x8000
	v_lshl_add_u64 v[2:3], v[2:3], 0, s[100:101]
	s_mov_b32 m0, s48
	s_add_u32 s10, s18, 0xa000
	global_load_lds_dwordx4 v[2:3], off
	v_lshl_add_u64 v[2:3], v[4:5], 0, s[100:101]
	s_mov_b32 m0, s49
	s_addc_u32 s11, s19, 0
	global_load_lds_dwordx4 v[2:3], off
	s_add_i32 m0, s42, 0x1c000
	v_lshl_add_u64 v[2:3], s[10:11], 0, v[0:1]
	global_load_lds_dwordx4 v[2:3], off
	v_lshl_add_u64 v[2:3], s[10:11], 0, v[130:131]
	s_add_i32 m0, s42, 0x1e000
	s_movk_i32 s15, 0x1600
	global_load_lds_dwordx4 v[2:3], off
	v_lshrrev_b32_e32 v3, 1, v10
	v_mul_lo_u32 v2, v11, s15
	s_mov_b32 s14, 0x16000
	s_cmpk_lt_u32 s12, 0x100
	v_lshl_or_b32 v160, v19, 2, s13
	v_mad_u64_u32 v[2:3], s[12:13], v3, s14, v[2:3]
	v_or_b32_e32 v2, v2, v12
	v_add_lshl_u32 v2, v2, v13, 1
	v_mov_b32_e32 v3, v1
	s_mov_b64 s[20:21], 0x160080
	s_mov_b64 s[100:101], 0xa000
	v_lshl_add_u64 v[132:133], v[228:229], 0, s[100:101]
	v_lshrrev_b32_e32 v3, 1, v15
	v_mul_lo_u32 v2, v14, s15
	v_mad_u64_u32 v[2:3], s[12:13], v3, s14, v[2:3]
	s_waitcnt vmcnt(6)
	v_or_b32_e32 v2, v2, v16
	v_add_lshl_u32 v2, v2, v17, 1
	v_mov_b32_e32 v3, v1
	v_readlane_b32 s12, v255, 17
	s_cselect_b64 s[10:11], -1, 0
	v_lshl_add_u64 v[134:135], v[226:227], 0, s[100:101]
	s_mov_b32 s50, 0
	v_add_u32_e32 v161, 0, v21
	v_readlane_b32 s26, v255, 21
	s_mov_b32 s55, s12
	s_barrier
	v_readlane_b32 s13, v255, 18
	s_branch .LBB0_347

; #define PG8_STAGE(bufoff, gbase, voff) do { _Pragma("unroll") for (int _i = 0; _i < 2; ++_i) \
;         __builtin_amdgcn_global_load_lds((const unsigned*)((const char*)(gbase) + (voff)[_i]), (PG8_LAS unsigned*)(lds + (bufoff) + ldsw + _i * 8192), 16, 0, 0); } while (0)
; #define PG8_LDA(dst, b, h) do { _Pragma("unroll") for (int m = 0; m < 4; ++m) _Pragma("unroll") for (int k = 0; k < 2; ++k) dst[m][k] = *(const PG8_LAS bf16x8*)(lds + PG8_SA(b, h) + aoff + m * 2048 + k * 1024); } while (0)
; #define PG8_LDB(dst, b, h) do { _Pragma("unroll") for (int n = 0; n < 2; ++n) _Pragma("unroll") for (int k = 0; k < 2; ++k) dst[n][k] = *(const PG8_LAS bf16x8*)(lds + PG8_SB(b, h) + boff + n * 2048 + k * 1024); } while (0)
; #define PG8_WAIT_V(n) asm volatile("s_waitcnt vmcnt(" #n ")" ::: "memory")
; #define PG8_WAIT_L(n) asm volatile("s_waitcnt lgkmcnt(" #n ")" ::: "memory")
; template <class Epi, class Sched, bool ALIGN_EPI = false, bool SP2 = false>
; __device__ __forceinline__ void gemm_phase(PG8_LAS unsigned char* lds, const Gemm g, const Sched& S, const Epi& E, int wave_s) {
;     ...
;     for (;;) {
;         const bool has_next = S.next(ui + 1, nxt);
;         const char* nA = has_next ? (const char*)g.A + (size_t)nxt.pm * tstepA : cA; const char* nB = has_next ? (const char*)g.Bt + (size_t)nxt.pn * tstepB : cB;
;         for (int t = 0; t < nt; t += 2) {
;             const bool last = (t == nt - 2);
;             const char* a1 = cA + (size_t)(t + 1) * kstep;
;             const char* a2 = last ? nA : cA + (size_t)(t + 2) * kstep; const char* b2 = last ? nB : cB + (size_t)(t + 2) * kstep;
;             const char* a3 = a2 + kstep; const char* b3 = b2 + kstep;
;             if (last && has_next) S.a_ready(nxt);
;             if constexpr (Epi::HAS_MID) { if (t == nt / 2) E.mid(acc, cur, wr, wc, fr, fq); }
;             if constexpr (SP2) {
;             PG8_LDB(B0, 0, 0); PG8_LDB(B1, 0, 1); PG8_SCHED; PG8_LDA(At, 0, 0); PG8_STAGE(PG8_SA(1, 1), a1 + hstepA, voffA);
;             PG8_WAIT_V(8); PG8_WAIT_L(0); PG8_BAR; PG8_MMA(0, 0, At, B0); PG8_MMA(0, 1, At, B1); PG8_BAR; PG8_SCHED;
;             PG8_LDA(At, 0, 1); PG8_STAGE(PG8_SB(0, 0), b2, voffB); PG8_STAGE(PG8_SB(0, 1), b2 + hstepB, voffB); PG8_STAGE(PG8_SA(0, 0), a2, voffA);
;             PG8_WAIT_V(8); PG8_WAIT_L(0); PG8_BAR; PG8_MMA(1, 0, At, B0); PG8_MMA(1, 1, At, B1); PG8_BAR; PG8_SCHED;
.LBB0_358:
	s_add_u32 s18, s16, 0x10000
	s_addc_u32 s19, s17, 0
	s_add_i32 s34, 0, 0x10000
	s_cmpk_eq_i32 s41, 0x54
	s_cselect_b32 s25, s13, s19
	s_cselect_b32 s24, s12, s18
	s_cselect_b32 s21, s15, s40
	s_cselect_b32 s20, s14, s27
	s_add_i32 s35, 0, 0x14000
	v_add_u32_e32 v148, s34, v159
	v_add_u32_e32 v156, s35, v159
	ds_read_b128 v[136:139], v148
	ds_read_b128 v[140:143], v148 offset:1024
	ds_read_b128 v[144:147], v148 offset:2048
	ds_read_b128 v[148:151], v148 offset:3072
	ds_read_b128 v[152:155], v156
	ds_read_b128 v[162:165], v156 offset:1024
	ds_read_b128 v[166:169], v156 offset:2048
	ds_read_b128 v[176:179], v156 offset:3072
	v_lshl_add_u64 v[156:157], s[16:17], 0, v[134:135]
	s_add_i32 m0, s42, 0xc000
	ds_read_b128 v[180:183], v161
	ds_read_b128 v[184:187], v161 offset:1024
	ds_read_b128 v[188:191], v161 offset:2048
	ds_read_b128 v[192:195], v161 offset:3072
	ds_read_b128 v[196:199], v161 offset:4096
	ds_read_b128 v[208:211], v161 offset:5120
	ds_read_b128 v[212:215], v161 offset:6144
	ds_read_b128 v[216:219], v161 offset:7168
	global_load_lds_dwordx4 v[156:157], off
	v_lshl_add_u64 v[156:157], s[16:17], 0, v[132:133]
	s_add_i32 m0, s42, 0xe000
	s_nop 0
	global_load_lds_dwordx4 v[156:157], off
	s_waitcnt vmcnt(8)
	s_waitcnt lgkmcnt(0)
	s_barrier
	s_setprio 1
	s_waitcnt lgkmcnt(0)
	v_mfma_f32_16x16x32_bf16 v[126:129], v[180:183], v[136:139], v[126:129]
	v_mfma_f32_16x16x32_bf16 v[122:125], v[180:183], v[144:147], v[122:125]
	v_mfma_f32_16x16x32_bf16 v[110:113], v[188:191], v[136:139], v[110:113]
	v_mfma_f32_16x16x32_bf16 v[106:109], v[188:191], v[144:147], v[106:109]
	v_mfma_f32_16x16x32_bf16 v[94:97], v[196:199], v[136:139], v[94:97]
	v_mfma_f32_16x16x32_bf16 v[90:93], v[196:199], v[144:147], v[90:93]
	v_mfma_f32_16x16x32_bf16 v[78:81], v[212:215], v[136:139], v[78:81]
	v_mfma_f32_16x16x32_bf16 v[74:77], v[212:215], v[144:147], v[74:77]
	v_mfma_f32_16x16x32_bf16 v[126:129], v[184:187], v[140:143], v[126:129]
	v_mfma_f32_16x16x32_bf16 v[122:125], v[184:187], v[148:151], v[122:125]
	v_mfma_f32_16x16x32_bf16 v[110:113], v[192:195], v[140:143], v[110:113]
	v_mfma_f32_16x16x32_bf16 v[106:109], v[192:195], v[148:151], v[106:109]
	v_mfma_f32_16x16x32_bf16 v[94:97], v[208:211], v[140:143], v[94:97]
	v_mfma_f32_16x16x32_bf16 v[90:93], v[208:211], v[148:151], v[90:93]
	v_mfma_f32_16x16x32_bf16 v[78:81], v[216:219], v[140:143], v[78:81]
	v_mfma_f32_16x16x32_bf16 v[74:77], v[216:219], v[148:151], v[74:77]
	s_setprio 0
	s_setprio 1
	v_mfma_f32_16x16x32_bf16 v[118:121], v[180:183], v[152:155], v[118:121]
	v_mfma_f32_16x16x32_bf16 v[114:117], v[180:183], v[166:169], v[114:117]
	v_mfma_f32_16x16x32_bf16 v[102:105], v[188:191], v[152:155], v[102:105]
	v_mfma_f32_16x16x32_bf16 v[98:101], v[188:191], v[166:169], v[98:101]
	v_mfma_f32_16x16x32_bf16 v[86:89], v[196:199], v[152:155], v[86:89]
	v_mfma_f32_16x16x32_bf16 v[82:85], v[196:199], v[166:169], v[82:85]
	v_mfma_f32_16x16x32_bf16 v[70:73], v[212:215], v[152:155], v[70:73]
	v_mfma_f32_16x16x32_bf16 v[66:69], v[212:215], v[166:169], v[66:69]
	v_mfma_f32_16x16x32_bf16 v[118:121], v[184:187], v[162:165], v[118:121]
	v_mfma_f32_16x16x32_bf16 v[114:117], v[184:187], v[176:179], v[114:117]
	v_mfma_f32_16x16x32_bf16 v[102:105], v[192:195], v[162:165], v[102:105]
	v_mfma_f32_16x16x32_bf16 v[98:101], v[192:195], v[176:179], v[98:101]
	v_mfma_f32_16x16x32_bf16 v[86:89], v[208:211], v[162:165], v[86:89]
	v_mfma_f32_16x16x32_bf16 v[82:85], v[208:211], v[176:179], v[82:85]
	v_mfma_f32_16x16x32_bf16 v[70:73], v[216:219], v[162:165], v[70:73]
	v_mfma_f32_16x16x32_bf16 v[66:69], v[216:219], v[176:179], v[66:69]
	s_setprio 0
	s_barrier
	s_add_i32 s16, s34, s37
	v_lshl_add_u64 v[156:157], s[20:21], 0, v[0:1]
	s_mov_b32 m0, s16
	ds_read_b128 v[180:183], v161 offset:16384
	ds_read_b128 v[184:187], v161 offset:17408
	ds_read_b128 v[188:191], v161 offset:18432
	ds_read_b128 v[192:195], v161 offset:19456
	ds_read_b128 v[196:199], v161 offset:20480
	ds_read_b128 v[208:211], v161 offset:21504
	ds_read_b128 v[212:215], v161 offset:22528
	ds_read_b128 v[216:219], v161 offset:23552
	global_load_lds_dwordx4 v[156:157], off
	s_add_i32 m0, s16, 0x2000
	s_add_u32 s16, s20, 0x2000
	v_lshl_add_u64 v[170:171], s[20:21], 0, v[130:131]
	s_addc_u32 s17, s21, 0
	s_add_i32 s34, s35, s37
	global_load_lds_dwordx4 v[170:171], off
	v_lshl_add_u64 v[200:201], s[16:17], 0, v[0:1]
	s_mov_b32 m0, s34
	v_lshl_add_u64 v[220:221], s[24:25], 0, v[228:229]
	global_load_lds_dwordx4 v[200:201], off
	v_lshl_add_u64 v[200:201], s[16:17], 0, v[130:131]
	s_add_i32 m0, s34, 0x2000
	s_nop 0
	global_load_lds_dwordx4 v[200:201], off
	v_lshl_add_u64 v[200:201], s[24:25], 0, v[226:227]
	s_mov_b32 m0, s42
	s_nop 0
	global_load_lds_dwordx4 v[200:201], off
	s_mov_b32 m0, s43
	s_nop 0
	global_load_lds_dwordx4 v[220:221], off
	s_waitcnt vmcnt(8)
	s_waitcnt lgkmcnt(0)
	s_barrier
; #define PG8_STAGE(bufoff, gbase, voff) do { _Pragma("unroll") for (int _i = 0; _i < 2; ++_i) \
;         __builtin_amdgcn_global_load_lds((const unsigned*)((const char*)(gbase) + (voff)[_i]), (PG8_LAS unsigned*)(lds + (bufoff) + ldsw + _i * 8192), 16, 0, 0); } while (0)
; #define PG8_LDA(dst, b, h) do { _Pragma("unroll") for (int m = 0; m < 4; ++m) _Pragma("unroll") for (int k = 0; k < 2; ++k) dst[m][k] = *(const PG8_LAS bf16x8*)(lds + PG8_SA(b, h) + aoff + m * 2048 + k * 1024); } while (0)
; #define PG8_LDB(dst, b, h) do { _Pragma("unroll") for (int n = 0; n < 2; ++n) _Pragma("unroll") for (int k = 0; k < 2; ++k) dst[n][k] = *(const PG8_LAS bf16x8*)(lds + PG8_SB(b, h) + boff + n * 2048 + k * 1024); } while (0)
; #define PG8_MMA(ai, bj, At, Bt) do { __builtin_amdgcn_s_setprio(1); _Pragma("unroll") for (int m = 0; m < 4; ++m) _Pragma("unroll") for (int n = 0; n < 2; ++n) _Pragma("unroll") for (int k = 0; k < 2; ++k) \
;         acc[ai][bj][m][n] = __builtin_amdgcn_mfma_f32_16x16x32_bf16(Bt[n][k], At[m][k], acc[ai][bj][m][n], 0, 0, 0); __builtin_amdgcn_s_setprio(0); } while (0)
; #define PG8_WAIT_V(n) asm volatile("s_waitcnt vmcnt(" #n ")" ::: "memory")
; #define PG8_WAIT_L(n) asm volatile("s_waitcnt lgkmcnt(" #n ")" ::: "memory")
; #define PG8_BAR __builtin_amdgcn_s_barrier()
; #define PG8_SCHED __builtin_amdgcn_sched_barrier(0)
; template <class Epi, class Sched, bool ALIGN_EPI = false, bool SP2 = false>
; __device__ __forceinline__ void gemm_phase(PG8_LAS unsigned char* lds, const Gemm g, const Sched& S, const Epi& E, int wave_s) {
;     ...
;             PG8_WAIT_V(8); PG8_WAIT_L(0); PG8_BAR; PG8_MMA(0, 0, At, B0); PG8_MMA(0, 1, At, B1); PG8_BAR; PG8_SCHED;
;             PG8_LDA(At, 0, 1); PG8_STAGE(PG8_SB(0, 0), b2, voffB); PG8_STAGE(PG8_SB(0, 1), b2 + hstepB, voffB); PG8_STAGE(PG8_SA(0, 0), a2, voffA);
;             PG8_WAIT_V(8); PG8_WAIT_L(0); PG8_BAR; PG8_MMA(1, 0, At, B0); PG8_MMA(1, 1, At, B1); PG8_BAR; PG8_SCHED;
;             PG8_LDB(B0, 1, 0); PG8_LDB(B1, 1, 1); PG8_SCHED; PG8_LDA(At, 1, 0); PG8_STAGE(PG8_SA(0, 1), a2 + hstepA, voffA);
;             PG8_WAIT_V(8); PG8_WAIT_L(0); PG8_BAR; PG8_MMA(0, 0, At, B0); PG8_MMA(0, 1, At, B1); PG8_BAR; PG8_SCHED;
	s_setprio 1
	s_waitcnt lgkmcnt(0)
	v_mfma_f32_16x16x32_bf16 v[62:65], v[180:183], v[136:139], v[62:65]
	v_mfma_f32_16x16x32_bf16 v[58:61], v[180:183], v[144:147], v[58:61]
	v_mfma_f32_16x16x32_bf16 v[46:49], v[188:191], v[136:139], v[46:49]
	v_mfma_f32_16x16x32_bf16 v[42:45], v[188:191], v[144:147], v[42:45]
	v_mfma_f32_16x16x32_bf16 v[30:33], v[196:199], v[136:139], v[30:33]
	v_mfma_f32_16x16x32_bf16 v[26:29], v[196:199], v[144:147], v[26:29]
	v_mfma_f32_16x16x32_bf16 v[14:17], v[212:215], v[136:139], v[14:17]
	v_mfma_f32_16x16x32_bf16 v[10:13], v[212:215], v[144:147], v[10:13]
	v_mfma_f32_16x16x32_bf16 v[62:65], v[184:187], v[140:143], v[62:65]
	v_mfma_f32_16x16x32_bf16 v[58:61], v[184:187], v[148:151], v[58:61]
	v_mfma_f32_16x16x32_bf16 v[46:49], v[192:195], v[140:143], v[46:49]
	v_mfma_f32_16x16x32_bf16 v[42:45], v[192:195], v[148:151], v[42:45]
	v_mfma_f32_16x16x32_bf16 v[30:33], v[208:211], v[140:143], v[30:33]
	v_mfma_f32_16x16x32_bf16 v[26:29], v[208:211], v[148:151], v[26:29]
	v_mfma_f32_16x16x32_bf16 v[14:17], v[216:219], v[140:143], v[14:17]
	v_mfma_f32_16x16x32_bf16 v[10:13], v[216:219], v[148:151], v[10:13]
	s_setprio 0
	s_setprio 1
	v_mfma_f32_16x16x32_bf16 v[54:57], v[180:183], v[152:155], v[54:57]
	v_mfma_f32_16x16x32_bf16 v[50:53], v[180:183], v[166:169], v[50:53]
	v_mfma_f32_16x16x32_bf16 v[38:41], v[188:191], v[152:155], v[38:41]
	v_mfma_f32_16x16x32_bf16 v[34:37], v[188:191], v[166:169], v[34:37]
	v_mfma_f32_16x16x32_bf16 v[22:25], v[196:199], v[152:155], v[22:25]
	v_mfma_f32_16x16x32_bf16 v[18:21], v[196:199], v[166:169], v[18:21]
	v_mfma_f32_16x16x32_bf16 v[6:9], v[212:215], v[152:155], v[6:9]
	v_mfma_f32_16x16x32_bf16 v[2:5], v[212:215], v[166:169], v[2:5]
	v_mfma_f32_16x16x32_bf16 v[54:57], v[184:187], v[162:165], v[54:57]
	v_mfma_f32_16x16x32_bf16 v[50:53], v[184:187], v[176:179], v[50:53]
	v_mfma_f32_16x16x32_bf16 v[38:41], v[192:195], v[162:165], v[38:41]
	v_mfma_f32_16x16x32_bf16 v[34:37], v[192:195], v[176:179], v[34:37]
	v_mfma_f32_16x16x32_bf16 v[22:25], v[208:211], v[162:165], v[22:25]
	v_mfma_f32_16x16x32_bf16 v[18:21], v[208:211], v[176:179], v[18:21]
	v_mfma_f32_16x16x32_bf16 v[6:9], v[216:219], v[162:165], v[6:9]
	v_mfma_f32_16x16x32_bf16 v[2:5], v[216:219], v[176:179], v[2:5]
	s_setprio 0
	s_barrier
	s_add_i32 s34, 0, 0x18000
	s_add_i32 s35, 0, 0x1c000
	v_add_u32_e32 v148, s34, v159
	v_add_u32_e32 v176, s35, v159
	ds_read_b128 v[136:139], v148
	ds_read_b128 v[140:143], v148 offset:1024
	ds_read_b128 v[144:147], v148 offset:2048
	ds_read_b128 v[148:151], v148 offset:3072
	ds_read_b128 v[152:155], v176
	ds_read_b128 v[162:165], v176 offset:1024
	ds_read_b128 v[166:169], v176 offset:2048
	ds_read_b128 v[176:179], v176 offset:3072
	s_add_u32 s16, s24, 0x2000
	s_addc_u32 s17, s25, 0
	s_mov_b32 m0, s44
	v_lshl_add_u64 v[222:223], s[16:17], 0, v[226:227]
	ds_read_b128 v[180:183], v161 offset:32768
	ds_read_b128 v[184:187], v161 offset:33792
	ds_read_b128 v[188:191], v161 offset:34816
	ds_read_b128 v[192:195], v161 offset:35840
	ds_read_b128 v[196:199], v161 offset:36864
	ds_read_b128 v[208:211], v161 offset:37888
	ds_read_b128 v[212:215], v161 offset:38912
	ds_read_b128 v[216:219], v161 offset:39936
	global_load_lds_dwordx4 v[222:223], off
	v_lshl_add_u64 v[222:223], s[16:17], 0, v[228:229]
	s_mov_b32 m0, s45
	s_nop 0
	global_load_lds_dwordx4 v[222:223], off
	s_waitcnt vmcnt(8)
	s_waitcnt lgkmcnt(0)
	s_barrier
	s_setprio 1
	s_waitcnt lgkmcnt(0)
	v_mfma_f32_16x16x32_bf16 v[126:129], v[180:183], v[136:139], v[126:129]
	v_mfma_f32_16x16x32_bf16 v[122:125], v[180:183], v[144:147], v[122:125]
	v_mfma_f32_16x16x32_bf16 v[110:113], v[188:191], v[136:139], v[110:113]
	v_mfma_f32_16x16x32_bf16 v[106:109], v[188:191], v[144:147], v[106:109]
	v_mfma_f32_16x16x32_bf16 v[94:97], v[196:199], v[136:139], v[94:97]
	v_mfma_f32_16x16x32_bf16 v[90:93], v[196:199], v[144:147], v[90:93]
	v_mfma_f32_16x16x32_bf16 v[78:81], v[212:215], v[136:139], v[78:81]
	v_mfma_f32_16x16x32_bf16 v[74:77], v[212:215], v[144:147], v[74:77]
	v_mfma_f32_16x16x32_bf16 v[126:129], v[184:187], v[140:143], v[126:129]
	v_mfma_f32_16x16x32_bf16 v[122:125], v[184:187], v[148:151], v[122:125]
	v_mfma_f32_16x16x32_bf16 v[110:113], v[192:195], v[140:143], v[110:113]
	v_mfma_f32_16x16x32_bf16 v[106:109], v[192:195], v[148:151], v[106:109]
	v_mfma_f32_16x16x32_bf16 v[94:97], v[208:211], v[140:143], v[94:97]
	v_mfma_f32_16x16x32_bf16 v[90:93], v[208:211], v[148:151], v[90:93]
	v_mfma_f32_16x16x32_bf16 v[78:81], v[216:219], v[140:143], v[78:81]
	v_mfma_f32_16x16x32_bf16 v[74:77], v[216:219], v[148:151], v[74:77]
	s_setprio 0
	s_setprio 1
	v_mfma_f32_16x16x32_bf16 v[118:121], v[180:183], v[152:155], v[118:121]
	v_mfma_f32_16x16x32_bf16 v[114:117], v[180:183], v[166:169], v[114:117]
	v_mfma_f32_16x16x32_bf16 v[102:105], v[188:191], v[152:155], v[102:105]
	v_mfma_f32_16x16x32_bf16 v[98:101], v[188:191], v[166:169], v[98:101]
	v_mfma_f32_16x16x32_bf16 v[86:89], v[196:199], v[152:155], v[86:89]
	v_mfma_f32_16x16x32_bf16 v[82:85], v[196:199], v[166:169], v[82:85]
	v_mfma_f32_16x16x32_bf16 v[70:73], v[212:215], v[152:155], v[70:73]
	v_mfma_f32_16x16x32_bf16 v[66:69], v[212:215], v[166:169], v[66:69]
	v_mfma_f32_16x16x32_bf16 v[118:121], v[184:187], v[162:165], v[118:121]
	v_mfma_f32_16x16x32_bf16 v[114:117], v[184:187], v[176:179], v[114:117]
	v_mfma_f32_16x16x32_bf16 v[102:105], v[192:195], v[162:165], v[102:105]
	v_mfma_f32_16x16x32_bf16 v[98:101], v[192:195], v[176:179], v[98:101]
	v_mfma_f32_16x16x32_bf16 v[86:89], v[208:211], v[162:165], v[86:89]
	v_mfma_f32_16x16x32_bf16 v[82:85], v[208:211], v[176:179], v[82:85]
	v_mfma_f32_16x16x32_bf16 v[70:73], v[216:219], v[162:165], v[70:73]
	v_mfma_f32_16x16x32_bf16 v[66:69], v[216:219], v[176:179], v[66:69]
	s_setprio 0
	s_barrier
; #define PG8_STAGE(bufoff, gbase, voff) do { _Pragma("unroll") for (int _i = 0; _i < 2; ++_i) \
;         __builtin_amdgcn_global_load_lds((const unsigned*)((const char*)(gbase) + (voff)[_i]), (PG8_LAS unsigned*)(lds + (bufoff) + ldsw + _i * 8192), 16, 0, 0); } while (0)
; #define PG8_LDA(dst, b, h) do { _Pragma("unroll") for (int m = 0; m < 4; ++m) _Pragma("unroll") for (int k = 0; k < 2; ++k) dst[m][k] = *(const PG8_LAS bf16x8*)(lds + PG8_SA(b, h) + aoff + m * 2048 + k * 1024); } while (0)
; #define PG8_WAIT_V(n) asm volatile("s_waitcnt vmcnt(" #n ")" ::: "memory")
; #define PG8_BAR __builtin_amdgcn_s_barrier()
; template <class Epi, class Sched, bool ALIGN_EPI = false, bool SP2 = false>
; __device__ __forceinline__ void gemm_phase(PG8_LAS unsigned char* lds, const Gemm g, const Sched& S, const Epi& E, int wave_s) {
;     ...
;         for (int t = 0; t < nt; t += 2) {
;             const bool last = (t == nt - 2);
;             const char* a1 = cA + (size_t)(t + 1) * kstep;
;             const char* a2 = last ? nA : cA + (size_t)(t + 2) * kstep; const char* b2 = last ? nB : cB + (size_t)(t + 2) * kstep;
;             const char* a3 = a2 + kstep; const char* b3 = b2 + kstep;
;             if (last && has_next) S.a_ready(nxt);
;             if constexpr (Epi::HAS_MID) { if (t == nt / 2) E.mid(acc, cur, wr, wc, fr, fq); }
;             if constexpr (SP2) {
;             PG8_LDB(B0, 0, 0); PG8_LDB(B1, 0, 1); PG8_SCHED; PG8_LDA(At, 0, 0); PG8_STAGE(PG8_SA(1, 1), a1 + hstepA, voffA);
;             PG8_WAIT_V(8); PG8_WAIT_L(0); PG8_BAR; PG8_MMA(0, 0, At, B0); PG8_MMA(0, 1, At, B1); PG8_BAR; PG8_SCHED;
;             PG8_LDA(At, 0, 1); PG8_STAGE(PG8_SB(0, 0), b2, voffB); PG8_STAGE(PG8_SB(0, 1), b2 + hstepB, voffB); PG8_STAGE(PG8_SA(0, 0), a2, voffA);
;             PG8_WAIT_V(8); PG8_WAIT_L(0); PG8_BAR; PG8_MMA(1, 0, At, B0); PG8_MMA(1, 1, At, B1); PG8_BAR; PG8_SCHED;
;             PG8_LDB(B0, 1, 0); PG8_LDB(B1, 1, 1); PG8_SCHED; PG8_LDA(At, 1, 0); PG8_STAGE(PG8_SA(0, 1), a2 + hstepA, voffA);
;             PG8_WAIT_V(8); PG8_WAIT_L(0); PG8_BAR; PG8_MMA(0, 0, At, B0); PG8_MMA(0, 1, At, B1); PG8_BAR; PG8_SCHED;
;             PG8_LDA(At, 1, 1); PG8_STAGE(PG8_SB(1, 0), b3, voffB); PG8_STAGE(PG8_SB(1, 1), b3 + hstepB, voffB); PG8_STAGE(PG8_SA(1, 0), a3, voffA);
;             PG8_WAIT_V(8); PG8_WAIT_L(0); PG8_BAR; PG8_MMA(1, 0, At, B0); PG8_MMA(1, 1, At, B1); PG8_BAR; PG8_SCHED;
	s_add_i32 s16, s34, s37
	s_mov_b64 s[100:101], 0x8000
	v_lshl_add_u64 v[156:157], v[156:157], 0, s[100:101]
	s_mov_b32 m0, s16
	ds_read_b128 v[180:183], v161 offset:49152
	ds_read_b128 v[184:187], v161 offset:50176
	ds_read_b128 v[188:191], v161 offset:51200
	ds_read_b128 v[192:195], v161 offset:52224
	ds_read_b128 v[196:199], v161 offset:53248
	ds_read_b128 v[208:211], v161 offset:54272
	ds_read_b128 v[212:215], v161 offset:55296
	ds_read_b128 v[216:219], v161 offset:56320
	global_load_lds_dwordx4 v[156:157], off
	s_add_i32 m0, s16, 0x2000
	s_add_u32 s16, s20, 0xa000
	v_lshl_add_u64 v[156:157], v[170:171], 0, s[100:101]
	s_addc_u32 s17, s21, 0
	s_add_i32 s20, s35, s37
	global_load_lds_dwordx4 v[156:157], off
	v_lshl_add_u64 v[156:157], s[16:17], 0, v[0:1]
	s_mov_b32 m0, s20
	s_nop 0
	global_load_lds_dwordx4 v[156:157], off
	v_lshl_add_u64 v[156:157], s[16:17], 0, v[130:131]
	s_add_i32 m0, s20, 0x2000
	s_nop 0
	global_load_lds_dwordx4 v[156:157], off
	s_mov_b64 s[100:101], 0x8000
	v_lshl_add_u64 v[156:157], v[200:201], 0, s[100:101]
	s_mov_b32 m0, s48
	s_nop 0
	global_load_lds_dwordx4 v[156:157], off
	v_lshl_add_u64 v[156:157], v[220:221], 0, s[100:101]
	s_mov_b32 m0, s49
	s_nop 0
	global_load_lds_dwordx4 v[156:157], off
	s_waitcnt vmcnt(8)
	s_waitcnt lgkmcnt(0)
	s_barrier
	s_setprio 1
	s_waitcnt lgkmcnt(0)
	v_mfma_f32_16x16x32_bf16 v[62:65], v[180:183], v[136:139], v[62:65]
	v_mfma_f32_16x16x32_bf16 v[58:61], v[180:183], v[144:147], v[58:61]
	v_mfma_f32_16x16x32_bf16 v[46:49], v[188:191], v[136:139], v[46:49]
	v_mfma_f32_16x16x32_bf16 v[42:45], v[188:191], v[144:147], v[42:45]
	v_mfma_f32_16x16x32_bf16 v[30:33], v[196:199], v[136:139], v[30:33]
	v_mfma_f32_16x16x32_bf16 v[26:29], v[196:199], v[144:147], v[26:29]
	v_mfma_f32_16x16x32_bf16 v[14:17], v[212:215], v[136:139], v[14:17]
	v_mfma_f32_16x16x32_bf16 v[10:13], v[212:215], v[144:147], v[10:13]
	v_mfma_f32_16x16x32_bf16 v[62:65], v[184:187], v[140:143], v[62:65]
	v_mfma_f32_16x16x32_bf16 v[58:61], v[184:187], v[148:151], v[58:61]
	v_mfma_f32_16x16x32_bf16 v[46:49], v[192:195], v[140:143], v[46:49]
	v_mfma_f32_16x16x32_bf16 v[42:45], v[192:195], v[148:151], v[42:45]
	v_mfma_f32_16x16x32_bf16 v[30:33], v[208:211], v[140:143], v[30:33]
	v_mfma_f32_16x16x32_bf16 v[26:29], v[208:211], v[148:151], v[26:29]
	v_mfma_f32_16x16x32_bf16 v[14:17], v[216:219], v[140:143], v[14:17]
	v_mfma_f32_16x16x32_bf16 v[10:13], v[216:219], v[148:151], v[10:13]
	s_setprio 0
	s_setprio 1
	v_mfma_f32_16x16x32_bf16 v[54:57], v[180:183], v[152:155], v[54:57]
	v_mfma_f32_16x16x32_bf16 v[50:53], v[180:183], v[166:169], v[50:53]
	v_mfma_f32_16x16x32_bf16 v[38:41], v[188:191], v[152:155], v[38:41]
	v_mfma_f32_16x16x32_bf16 v[34:37], v[188:191], v[166:169], v[34:37]
	v_mfma_f32_16x16x32_bf16 v[22:25], v[196:199], v[152:155], v[22:25]
	v_mfma_f32_16x16x32_bf16 v[18:21], v[196:199], v[166:169], v[18:21]
	v_mfma_f32_16x16x32_bf16 v[6:9], v[212:215], v[152:155], v[6:9]
	v_mfma_f32_16x16x32_bf16 v[2:5], v[212:215], v[166:169], v[2:5]
	v_mfma_f32_16x16x32_bf16 v[54:57], v[184:187], v[162:165], v[54:57]
	v_mfma_f32_16x16x32_bf16 v[50:53], v[184:187], v[176:179], v[50:53]
	v_mfma_f32_16x16x32_bf16 v[38:41], v[192:195], v[162:165], v[38:41]
	v_mfma_f32_16x16x32_bf16 v[34:37], v[192:195], v[176:179], v[34:37]
	v_mfma_f32_16x16x32_bf16 v[22:25], v[208:211], v[162:165], v[22:25]
	v_mfma_f32_16x16x32_bf16 v[18:21], v[208:211], v[176:179], v[18:21]
	v_mfma_f32_16x16x32_bf16 v[6:9], v[216:219], v[162:165], v[6:9]
	v_mfma_f32_16x16x32_bf16 v[2:5], v[216:219], v[176:179], v[2:5]
	s_setprio 0
	s_barrier
	s_add_i32 s41, s41, 2
	s_add_u32 s27, s27, 0x10000
	s_addc_u32 s40, s40, 0
	s_cmpk_gt_u32 s41, 0x55
	s_mov_b64 s[16:17], s[18:19]
	s_cbranch_scc0 .LBB0_358
	s_and_b64 vcc, exec, s[10:11]
	s_cbranch_vccz .LBB0_361
	s_barrier

; __device__ __forceinline__ unsigned cvt_pk_bf16(float lo, float hi) { const pk_f2_t v = {lo, hi}; return __builtin_bit_cast(unsigned, __builtin_convertvector(v, pk_bf2_t)); }
; __device__ __forceinline__ float silu_f(float g) { return g * __builtin_amdgcn_rcpf(1.0f + __builtin_amdgcn_exp2f(-1.4426950408889634f * g)); }
;     __device__ __forceinline__ void operator()(const pg8::f32x4 (&acc)[2][2][4][2], const pg8::Unit& u, int wr, int wc, int fr, int fq) const {
;         const int row0 = u.pm * 256 + wr * 64 + fr, col0 = u.pn * 128 + wc * 32 + 8 * fq;
;         bf16* base = O + (size_t)row0 * FF + col0;
; #pragma unroll
;         for (int ai = 0; ai < 2; ++ai)
; #pragma unroll
;             for (int m = 0; m < 4; ++m) {
;                 pg8::u32x4 w;
;                 { const pg8::f32x4 g = acc[ai][0][m][0], uu = acc[ai][1][m][0];
;                   w.x = pg8::cvt_pk_bf16(silu_f(g[0]) * uu[0], silu_f(g[1]) * uu[1]); w.y = pg8::cvt_pk_bf16(silu_f(g[2]) * uu[2], silu_f(g[3]) * uu[3]); }
;                 { const pg8::f32x4 g = acc[ai][0][m][1], uu = acc[ai][1][m][1];
;                   w.z = pg8::cvt_pk_bf16(silu_f(g[0]) * uu[0], silu_f(g[1]) * uu[1]); w.w = pg8::cvt_pk_bf16(silu_f(g[2]) * uu[2], silu_f(g[3]) * uu[3]); }
;                 *(pg8::u32x4*)(base + (size_t)(ai * 128 + m * 16) * FF) = w;
;                 asm volatile("" ::: "memory");
;             }
.LBB0_1800:
	s_lshl_b32 s100, s26, 1
	v_lshrrev_b32_e32 v141, 6, v144
	v_add_u32_e32 v141, s100, v141
	v_lshlrev_b32_e32 v141, 15, v141
	v_bfe_u32 v140, v144, 5, 1
	v_lshl_or_b32 v141, v140, 14, v141
	v_and_b32_e32 v140, 31, v144
	v_lshlrev_b32_e32 v140, 1, v140
	v_lshl_add_u32 v140, v142, 6, v140
	v_add_u32_e32 v140, v140, v141
	s_mul_i32 s100, s27, 0x2c0000
	s_add_u32 s100, s6, s100
	s_addc_u32 s101, s7, 0
	v_mov_b32_e32 v141, 0
	v_lshl_add_u64 v[140:141], s[100:101], 0, v[140:141]
	s_mov_b64 s[18:19], -1
	v_mul_f32_e32 v150, 0xbfb8aa3b, v126
	v_mul_f32_e32 v151, 0xbfb8aa3b, v127
	v_mul_f32_e32 v152, 0xbfb8aa3b, v128
	v_mul_f32_e32 v153, 0xbfb8aa3b, v129
	v_mul_f32_e32 v154, 0xbfb8aa3b, v118
	v_mul_f32_e32 v155, 0xbfb8aa3b, v119
	v_mul_f32_e32 v156, 0xbfb8aa3b, v120
	v_mul_f32_e32 v157, 0xbfb8aa3b, v121
	v_exp_f32_e32 v150, v150
	v_exp_f32_e32 v151, v151
	v_exp_f32_e32 v152, v152
	v_exp_f32_e32 v153, v153
	v_exp_f32_e32 v154, v154
	v_exp_f32_e32 v155, v155
	v_exp_f32_e32 v156, v156
	v_exp_f32_e32 v157, v157
	v_add_f32_e32 v150, 1.0, v150
	v_add_f32_e32 v151, 1.0, v151
	v_add_f32_e32 v152, 1.0, v152
	v_add_f32_e32 v153, 1.0, v153
	v_add_f32_e32 v154, 1.0, v154
	v_add_f32_e32 v155, 1.0, v155
	v_add_f32_e32 v156, 1.0, v156
	v_add_f32_e32 v157, 1.0, v157
	v_rcp_f32_e32 v150, v150
	v_rcp_f32_e32 v151, v151
	v_rcp_f32_e32 v152, v152
	v_rcp_f32_e32 v153, v153
	v_rcp_f32_e32 v154, v154
	v_rcp_f32_e32 v155, v155
	v_rcp_f32_e32 v156, v156
	v_rcp_f32_e32 v157, v157
	v_mul_f32_e32 v150, v126, v150
	v_mul_f32_e32 v151, v127, v151
	v_mul_f32_e32 v152, v128, v152
	v_mul_f32_e32 v153, v129, v153
	v_mul_f32_e32 v154, v118, v154
	v_mul_f32_e32 v155, v119, v155
	v_mul_f32_e32 v156, v120, v156
	v_mul_f32_e32 v157, v121, v157
	v_mul_f32_e32 v122, v150, v122
	v_mul_f32_e32 v123, v151, v123
	v_mul_f32_e32 v124, v152, v124
	v_mul_f32_e32 v125, v153, v125
	v_mul_f32_e32 v114, v154, v114
	v_mul_f32_e32 v115, v155, v115
	v_mul_f32_e32 v116, v156, v116
	v_mul_f32_e32 v117, v157, v117
	v_cvt_pk_bf16_f32 v122, v122, v123
	v_cvt_pk_bf16_f32 v123, v124, v125
	v_cvt_pk_bf16_f32 v124, v114, v115
	v_cvt_pk_bf16_f32 v125, v116, v117
	flat_store_dwordx4 v[140:141], v[122:125]
	v_mul_f32_e32 v158, 0xbfb8aa3b, v110
	v_mul_f32_e32 v159, 0xbfb8aa3b, v111
	v_mul_f32_e32 v160, 0xbfb8aa3b, v112
	v_mul_f32_e32 v161, 0xbfb8aa3b, v113
	v_mul_f32_e32 v162, 0xbfb8aa3b, v102
	v_mul_f32_e32 v163, 0xbfb8aa3b, v103
	v_mul_f32_e32 v164, 0xbfb8aa3b, v104
	v_mul_f32_e32 v165, 0xbfb8aa3b, v105
	v_exp_f32_e32 v158, v158
	v_exp_f32_e32 v159, v159
	v_exp_f32_e32 v160, v160
	v_exp_f32_e32 v161, v161
	v_exp_f32_e32 v162, v162
	v_exp_f32_e32 v163, v163
	v_exp_f32_e32 v164, v164
	v_exp_f32_e32 v165, v165
	v_add_co_u32_e32 v166, vcc, 0x400, v140
	v_add_f32_e32 v158, 1.0, v158
	v_add_f32_e32 v159, 1.0, v159
	v_add_f32_e32 v160, 1.0, v160
	v_add_f32_e32 v161, 1.0, v161
	v_add_f32_e32 v162, 1.0, v162
	v_add_f32_e32 v163, 1.0, v163
	v_add_f32_e32 v164, 1.0, v164
	v_add_f32_e32 v165, 1.0, v165
	v_addc_co_u32_e32 v167, vcc, 0, v141, vcc
	v_rcp_f32_e32 v158, v158
	v_rcp_f32_e32 v159, v159
	v_rcp_f32_e32 v160, v160
	v_rcp_f32_e32 v161, v161
	v_rcp_f32_e32 v162, v162
	v_rcp_f32_e32 v163, v163
	v_rcp_f32_e32 v164, v164
	v_rcp_f32_e32 v165, v165
	v_mul_f32_e32 v158, v110, v158
	v_mul_f32_e32 v159, v111, v159
	v_mul_f32_e32 v160, v112, v160
	v_mul_f32_e32 v161, v113, v161
	v_mul_f32_e32 v162, v102, v162
	v_mul_f32_e32 v163, v103, v163
	v_mul_f32_e32 v164, v104, v164
	v_mul_f32_e32 v165, v105, v165
	v_mul_f32_e32 v106, v158, v106
	v_mul_f32_e32 v107, v159, v107
	v_mul_f32_e32 v108, v160, v108
	v_mul_f32_e32 v109, v161, v109
	v_mul_f32_e32 v98, v162, v98
	v_mul_f32_e32 v99, v163, v99
	v_mul_f32_e32 v100, v164, v100
	v_mul_f32_e32 v101, v165, v101
	v_cvt_pk_bf16_f32 v106, v106, v107
	v_cvt_pk_bf16_f32 v107, v108, v109
	v_cvt_pk_bf16_f32 v108, v98, v99
	v_cvt_pk_bf16_f32 v109, v100, v101
	flat_store_dwordx4 v[166:167], v[106:109]
	v_mul_f32_e32 v150, 0xbfb8aa3b, v94
	v_mul_f32_e32 v151, 0xbfb8aa3b, v95
	v_mul_f32_e32 v152, 0xbfb8aa3b, v96
	v_mul_f32_e32 v153, 0xbfb8aa3b, v97
	v_mul_f32_e32 v154, 0xbfb8aa3b, v86
	v_mul_f32_e32 v155, 0xbfb8aa3b, v87
	v_mul_f32_e32 v156, 0xbfb8aa3b, v88
	v_mul_f32_e32 v157, 0xbfb8aa3b, v89
	v_exp_f32_e32 v150, v150
	v_exp_f32_e32 v151, v151
	v_exp_f32_e32 v152, v152
	v_exp_f32_e32 v153, v153
	v_exp_f32_e32 v154, v154
	v_exp_f32_e32 v155, v155
	v_exp_f32_e32 v156, v156
	v_exp_f32_e32 v157, v157
	v_add_co_u32_e32 v148, vcc, 0x800, v140
	v_add_f32_e32 v150, 1.0, v150
	v_add_f32_e32 v151, 1.0, v151
	v_add_f32_e32 v152, 1.0, v152
	v_add_f32_e32 v153, 1.0, v153
	v_add_f32_e32 v154, 1.0, v154
	v_add_f32_e32 v155, 1.0, v155
	v_add_f32_e32 v156, 1.0, v156
	v_add_f32_e32 v157, 1.0, v157
	v_addc_co_u32_e32 v149, vcc, 0, v141, vcc
	v_rcp_f32_e32 v150, v150
	v_rcp_f32_e32 v151, v151
	v_rcp_f32_e32 v152, v152
	v_rcp_f32_e32 v153, v153
	v_rcp_f32_e32 v154, v154
	v_rcp_f32_e32 v155, v155
	v_rcp_f32_e32 v156, v156
	v_rcp_f32_e32 v157, v157
	v_mul_f32_e32 v150, v94, v150
	v_mul_f32_e32 v151, v95, v151
	v_mul_f32_e32 v152, v96, v152
	v_mul_f32_e32 v153, v97, v153
	v_mul_f32_e32 v154, v86, v154
	v_mul_f32_e32 v155, v87, v155
	v_mul_f32_e32 v156, v88, v156
	v_mul_f32_e32 v157, v89, v157
	v_mul_f32_e32 v90, v150, v90
	v_mul_f32_e32 v91, v151, v91
	v_mul_f32_e32 v92, v152, v92
	v_mul_f32_e32 v93, v153, v93
	v_mul_f32_e32 v82, v154, v82
	v_mul_f32_e32 v83, v155, v83
	v_mul_f32_e32 v84, v156, v84
	v_mul_f32_e32 v85, v157, v85
	v_cvt_pk_bf16_f32 v90, v90, v91
	v_cvt_pk_bf16_f32 v91, v92, v93
	v_cvt_pk_bf16_f32 v92, v82, v83
	v_cvt_pk_bf16_f32 v93, v84, v85
	flat_store_dwordx4 v[148:149], v[90:93]
; __device__ __forceinline__ unsigned cvt_pk_bf16(float lo, float hi) { const pk_f2_t v = {lo, hi}; return __builtin_bit_cast(unsigned, __builtin_convertvector(v, pk_bf2_t)); }
; __device__ __forceinline__ float silu_f(float g) { return g * __builtin_amdgcn_rcpf(1.0f + __builtin_amdgcn_exp2f(-1.4426950408889634f * g)); }
;     __device__ __forceinline__ void operator()(const pg8::f32x4 (&acc)[2][2][4][2], const pg8::Unit& u, int wr, int wc, int fr, int fq) const {
;     ...
;             for (int m = 0; m < 4; ++m) {
;                 pg8::u32x4 w;
;                 { const pg8::f32x4 g = acc[ai][0][m][0], uu = acc[ai][1][m][0];
;                   w.x = pg8::cvt_pk_bf16(silu_f(g[0]) * uu[0], silu_f(g[1]) * uu[1]); w.y = pg8::cvt_pk_bf16(silu_f(g[2]) * uu[2], silu_f(g[3]) * uu[3]); }
;                 { const pg8::f32x4 g = acc[ai][0][m][1], uu = acc[ai][1][m][1];
;                   w.z = pg8::cvt_pk_bf16(silu_f(g[0]) * uu[0], silu_f(g[1]) * uu[1]); w.w = pg8::cvt_pk_bf16(silu_f(g[2]) * uu[2], silu_f(g[3]) * uu[3]); }
;                 *(pg8::u32x4*)(base + (size_t)(ai * 128 + m * 16) * FF) = w;
	v_mul_f32_e32 v158, 0xbfb8aa3b, v78
	v_mul_f32_e32 v159, 0xbfb8aa3b, v79
	v_mul_f32_e32 v160, 0xbfb8aa3b, v80
	v_mul_f32_e32 v161, 0xbfb8aa3b, v81
	v_mul_f32_e32 v162, 0xbfb8aa3b, v70
	v_mul_f32_e32 v163, 0xbfb8aa3b, v71
	v_mul_f32_e32 v164, 0xbfb8aa3b, v72
	v_mul_f32_e32 v165, 0xbfb8aa3b, v73
	v_exp_f32_e32 v158, v158
	v_exp_f32_e32 v159, v159
	v_exp_f32_e32 v160, v160
	v_exp_f32_e32 v161, v161
	v_exp_f32_e32 v162, v162
	v_exp_f32_e32 v163, v163
	v_exp_f32_e32 v164, v164
	v_exp_f32_e32 v165, v165
	v_add_co_u32_e32 v166, vcc, 0xc00, v140
	v_add_f32_e32 v158, 1.0, v158
	v_add_f32_e32 v159, 1.0, v159
	v_add_f32_e32 v160, 1.0, v160
	v_add_f32_e32 v161, 1.0, v161
	v_add_f32_e32 v162, 1.0, v162
	v_add_f32_e32 v163, 1.0, v163
	v_add_f32_e32 v164, 1.0, v164
	v_add_f32_e32 v165, 1.0, v165
	v_addc_co_u32_e32 v167, vcc, 0, v141, vcc
	v_rcp_f32_e32 v158, v158
	v_rcp_f32_e32 v159, v159
	v_rcp_f32_e32 v160, v160
	v_rcp_f32_e32 v161, v161
	v_rcp_f32_e32 v162, v162
	v_rcp_f32_e32 v163, v163
	v_rcp_f32_e32 v164, v164
	v_rcp_f32_e32 v165, v165
	v_mul_f32_e32 v158, v78, v158
	v_mul_f32_e32 v159, v79, v159
	v_mul_f32_e32 v160, v80, v160
	v_mul_f32_e32 v161, v81, v161
	v_mul_f32_e32 v162, v70, v162
	v_mul_f32_e32 v163, v71, v163
	v_mul_f32_e32 v164, v72, v164
	v_mul_f32_e32 v165, v73, v165
	v_mul_f32_e32 v74, v158, v74
	v_mul_f32_e32 v75, v159, v75
	v_mul_f32_e32 v76, v160, v76
	v_mul_f32_e32 v77, v161, v77
	v_mul_f32_e32 v66, v162, v66
	v_mul_f32_e32 v67, v163, v67
	v_mul_f32_e32 v68, v164, v68
	v_mul_f32_e32 v69, v165, v69
	v_cvt_pk_bf16_f32 v74, v74, v75
	v_cvt_pk_bf16_f32 v75, v76, v77
	v_cvt_pk_bf16_f32 v76, v66, v67
	v_cvt_pk_bf16_f32 v77, v68, v69
	flat_store_dwordx4 v[166:167], v[74:77]
	v_mul_f32_e32 v150, 0xbfb8aa3b, v62
	v_mul_f32_e32 v151, 0xbfb8aa3b, v63
	v_mul_f32_e32 v152, 0xbfb8aa3b, v64
	v_mul_f32_e32 v153, 0xbfb8aa3b, v65
	v_mul_f32_e32 v154, 0xbfb8aa3b, v54
	v_mul_f32_e32 v155, 0xbfb8aa3b, v55
	v_mul_f32_e32 v156, 0xbfb8aa3b, v56
	v_mul_f32_e32 v157, 0xbfb8aa3b, v57
	v_exp_f32_e32 v150, v150
	v_exp_f32_e32 v151, v151
	v_exp_f32_e32 v152, v152
	v_exp_f32_e32 v153, v153
	v_exp_f32_e32 v154, v154
	v_exp_f32_e32 v155, v155
	v_exp_f32_e32 v156, v156
	v_exp_f32_e32 v157, v157
	v_add_co_u32_e32 v148, vcc, 0x2000, v140
	v_add_f32_e32 v150, 1.0, v150
	v_add_f32_e32 v151, 1.0, v151
	v_add_f32_e32 v152, 1.0, v152
	v_add_f32_e32 v153, 1.0, v153
	v_add_f32_e32 v154, 1.0, v154
	v_add_f32_e32 v155, 1.0, v155
	v_add_f32_e32 v156, 1.0, v156
	v_add_f32_e32 v157, 1.0, v157
	v_addc_co_u32_e32 v149, vcc, 0, v141, vcc
	v_rcp_f32_e32 v150, v150
	v_rcp_f32_e32 v151, v151
	v_rcp_f32_e32 v152, v152
	v_rcp_f32_e32 v153, v153
	v_rcp_f32_e32 v154, v154
	v_rcp_f32_e32 v155, v155
	v_rcp_f32_e32 v156, v156
	v_rcp_f32_e32 v157, v157
	v_mul_f32_e32 v150, v62, v150
	v_mul_f32_e32 v151, v63, v151
	v_mul_f32_e32 v152, v64, v152
	v_mul_f32_e32 v153, v65, v153
	v_mul_f32_e32 v154, v54, v154
	v_mul_f32_e32 v155, v55, v155
	v_mul_f32_e32 v156, v56, v156
	v_mul_f32_e32 v157, v57, v157
	v_mul_f32_e32 v58, v150, v58
	v_mul_f32_e32 v59, v151, v59
	v_mul_f32_e32 v60, v152, v60
	v_mul_f32_e32 v61, v153, v61
	v_mul_f32_e32 v50, v154, v50
	v_mul_f32_e32 v51, v155, v51
	v_mul_f32_e32 v52, v156, v52
	v_mul_f32_e32 v53, v157, v53
	v_cvt_pk_bf16_f32 v58, v58, v59
	v_cvt_pk_bf16_f32 v59, v60, v61
	v_cvt_pk_bf16_f32 v60, v50, v51
	v_cvt_pk_bf16_f32 v61, v52, v53
	flat_store_dwordx4 v[148:149], v[58:61]
	v_mul_f32_e32 v158, 0xbfb8aa3b, v46
	v_mul_f32_e32 v159, 0xbfb8aa3b, v47
	v_mul_f32_e32 v160, 0xbfb8aa3b, v48
	v_mul_f32_e32 v161, 0xbfb8aa3b, v49
	v_mul_f32_e32 v162, 0xbfb8aa3b, v38
	v_mul_f32_e32 v163, 0xbfb8aa3b, v39
	v_mul_f32_e32 v164, 0xbfb8aa3b, v40
	v_mul_f32_e32 v165, 0xbfb8aa3b, v41
	v_exp_f32_e32 v158, v158
	v_exp_f32_e32 v159, v159
	v_exp_f32_e32 v160, v160
	v_exp_f32_e32 v161, v161
	v_exp_f32_e32 v162, v162
	v_exp_f32_e32 v163, v163
	v_exp_f32_e32 v164, v164
	v_exp_f32_e32 v165, v165
	v_add_co_u32_e32 v166, vcc, 0x2400, v140
	v_add_f32_e32 v158, 1.0, v158
	v_add_f32_e32 v159, 1.0, v159
	v_add_f32_e32 v160, 1.0, v160
	v_add_f32_e32 v161, 1.0, v161
	v_add_f32_e32 v162, 1.0, v162
	v_add_f32_e32 v163, 1.0, v163
	v_add_f32_e32 v164, 1.0, v164
	v_add_f32_e32 v165, 1.0, v165
	v_addc_co_u32_e32 v167, vcc, 0, v141, vcc
	v_rcp_f32_e32 v158, v158
	v_rcp_f32_e32 v159, v159
	v_rcp_f32_e32 v160, v160
; __device__ __forceinline__ unsigned cvt_pk_bf16(float lo, float hi) { const pk_f2_t v = {lo, hi}; return __builtin_bit_cast(unsigned, __builtin_convertvector(v, pk_bf2_t)); }
; __device__ __forceinline__ float silu_f(float g) { return g * __builtin_amdgcn_rcpf(1.0f + __builtin_amdgcn_exp2f(-1.4426950408889634f * g)); }
;     __device__ __forceinline__ void operator()(const pg8::f32x4 (&acc)[2][2][4][2], const pg8::Unit& u, int wr, int wc, int fr, int fq) const {
;     ...
;             for (int m = 0; m < 4; ++m) {
;                 pg8::u32x4 w;
;                 { const pg8::f32x4 g = acc[ai][0][m][0], uu = acc[ai][1][m][0];
;                   w.x = pg8::cvt_pk_bf16(silu_f(g[0]) * uu[0], silu_f(g[1]) * uu[1]); w.y = pg8::cvt_pk_bf16(silu_f(g[2]) * uu[2], silu_f(g[3]) * uu[3]); }
;                 { const pg8::f32x4 g = acc[ai][0][m][1], uu = acc[ai][1][m][1];
;                   w.z = pg8::cvt_pk_bf16(silu_f(g[0]) * uu[0], silu_f(g[1]) * uu[1]); w.w = pg8::cvt_pk_bf16(silu_f(g[2]) * uu[2], silu_f(g[3]) * uu[3]); }
;                 *(pg8::u32x4*)(base + (size_t)(ai * 128 + m * 16) * FF) = w;
;                 asm volatile("" ::: "memory");
;             }
	v_rcp_f32_e32 v161, v161
	v_rcp_f32_e32 v162, v162
	v_rcp_f32_e32 v163, v163
	v_rcp_f32_e32 v164, v164
	v_rcp_f32_e32 v165, v165
	v_mul_f32_e32 v158, v46, v158
	v_mul_f32_e32 v159, v47, v159
	v_mul_f32_e32 v160, v48, v160
	v_mul_f32_e32 v161, v49, v161
	v_mul_f32_e32 v162, v38, v162
	v_mul_f32_e32 v163, v39, v163
	v_mul_f32_e32 v164, v40, v164
	v_mul_f32_e32 v165, v41, v165
	v_mul_f32_e32 v42, v158, v42
	v_mul_f32_e32 v43, v159, v43
	v_mul_f32_e32 v44, v160, v44
	v_mul_f32_e32 v45, v161, v45
	v_mul_f32_e32 v34, v162, v34
	v_mul_f32_e32 v35, v163, v35
	v_mul_f32_e32 v36, v164, v36
	v_mul_f32_e32 v37, v165, v37
	v_cvt_pk_bf16_f32 v42, v42, v43
	v_cvt_pk_bf16_f32 v43, v44, v45
	v_cvt_pk_bf16_f32 v44, v34, v35
	v_cvt_pk_bf16_f32 v45, v36, v37
	flat_store_dwordx4 v[166:167], v[42:45]
	v_mul_f32_e32 v150, 0xbfb8aa3b, v30
	v_mul_f32_e32 v151, 0xbfb8aa3b, v31
	v_mul_f32_e32 v152, 0xbfb8aa3b, v32
	v_mul_f32_e32 v153, 0xbfb8aa3b, v33
	v_mul_f32_e32 v154, 0xbfb8aa3b, v22
	v_mul_f32_e32 v155, 0xbfb8aa3b, v23
	v_mul_f32_e32 v156, 0xbfb8aa3b, v24
	v_mul_f32_e32 v157, 0xbfb8aa3b, v25
	v_exp_f32_e32 v150, v150
	v_exp_f32_e32 v151, v151
	v_exp_f32_e32 v152, v152
	v_exp_f32_e32 v153, v153
	v_exp_f32_e32 v154, v154
	v_exp_f32_e32 v155, v155
	v_exp_f32_e32 v156, v156
	v_exp_f32_e32 v157, v157
	v_add_co_u32_e32 v148, vcc, 0x2800, v140
	v_add_f32_e32 v150, 1.0, v150
	v_add_f32_e32 v151, 1.0, v151
	v_add_f32_e32 v152, 1.0, v152
	v_add_f32_e32 v153, 1.0, v153
	v_add_f32_e32 v154, 1.0, v154
	v_add_f32_e32 v155, 1.0, v155
	v_add_f32_e32 v156, 1.0, v156
	v_add_f32_e32 v157, 1.0, v157
	v_addc_co_u32_e32 v149, vcc, 0, v141, vcc
	v_rcp_f32_e32 v150, v150
	v_rcp_f32_e32 v151, v151
	v_rcp_f32_e32 v152, v152
	v_rcp_f32_e32 v153, v153
	v_rcp_f32_e32 v154, v154
	v_rcp_f32_e32 v155, v155
	v_rcp_f32_e32 v156, v156
	v_rcp_f32_e32 v157, v157
	v_mul_f32_e32 v150, v30, v150
	v_mul_f32_e32 v151, v31, v151
	v_mul_f32_e32 v152, v32, v152
	v_mul_f32_e32 v153, v33, v153
	v_mul_f32_e32 v154, v22, v154
	v_mul_f32_e32 v155, v23, v155
	v_mul_f32_e32 v156, v24, v156
	v_mul_f32_e32 v157, v25, v157
	v_mul_f32_e32 v26, v150, v26
	v_mul_f32_e32 v27, v151, v27
	v_mul_f32_e32 v28, v152, v28
	v_mul_f32_e32 v29, v153, v29
	v_mul_f32_e32 v18, v154, v18
	v_mul_f32_e32 v19, v155, v19
	v_mul_f32_e32 v20, v156, v20
	v_mul_f32_e32 v21, v157, v21
	v_cvt_pk_bf16_f32 v26, v26, v27
	v_cvt_pk_bf16_f32 v27, v28, v29
	v_cvt_pk_bf16_f32 v28, v18, v19
	v_cvt_pk_bf16_f32 v29, v20, v21
	flat_store_dwordx4 v[148:149], v[26:29]
	v_mul_f32_e32 v158, 0xbfb8aa3b, v14
	v_mul_f32_e32 v159, 0xbfb8aa3b, v15
	v_mul_f32_e32 v160, 0xbfb8aa3b, v16
	v_mul_f32_e32 v161, 0xbfb8aa3b, v17
	v_mul_f32_e32 v162, 0xbfb8aa3b, v6
	v_mul_f32_e32 v163, 0xbfb8aa3b, v7
	v_mul_f32_e32 v164, 0xbfb8aa3b, v8
	v_mul_f32_e32 v165, 0xbfb8aa3b, v9
	v_exp_f32_e32 v158, v158
	v_exp_f32_e32 v159, v159
	v_exp_f32_e32 v160, v160
	v_exp_f32_e32 v161, v161
	v_exp_f32_e32 v162, v162
	v_exp_f32_e32 v163, v163
	v_exp_f32_e32 v164, v164
	v_exp_f32_e32 v165, v165
	v_add_co_u32_e32 v166, vcc, 0x2c00, v140
	v_add_f32_e32 v158, 1.0, v158
	v_add_f32_e32 v159, 1.0, v159
	v_add_f32_e32 v160, 1.0, v160
	v_add_f32_e32 v161, 1.0, v161
	v_add_f32_e32 v162, 1.0, v162
	v_add_f32_e32 v163, 1.0, v163
	v_add_f32_e32 v164, 1.0, v164
	v_add_f32_e32 v165, 1.0, v165
	v_addc_co_u32_e32 v167, vcc, 0, v141, vcc
	v_rcp_f32_e32 v158, v158
	v_rcp_f32_e32 v159, v159
	v_rcp_f32_e32 v160, v160
	v_rcp_f32_e32 v161, v161
	v_rcp_f32_e32 v162, v162
	v_rcp_f32_e32 v163, v163
	v_rcp_f32_e32 v164, v164
	v_rcp_f32_e32 v165, v165
	v_mul_f32_e32 v158, v14, v158
	v_mul_f32_e32 v159, v15, v159
	v_mul_f32_e32 v160, v16, v160
	v_mul_f32_e32 v161, v17, v161
	v_mul_f32_e32 v162, v6, v162
	v_mul_f32_e32 v163, v7, v163
	v_mul_f32_e32 v164, v8, v164
	v_mul_f32_e32 v165, v9, v165
	v_mul_f32_e32 v10, v158, v10
	v_mul_f32_e32 v11, v159, v11
	v_mul_f32_e32 v12, v160, v12
	v_mul_f32_e32 v13, v161, v13
	v_mul_f32_e32 v2, v162, v2
	v_mul_f32_e32 v3, v163, v3
	v_mul_f32_e32 v4, v164, v4
	v_mul_f32_e32 v5, v165, v5
	v_cvt_pk_bf16_f32 v10, v10, v11
	v_cvt_pk_bf16_f32 v11, v12, v13
	v_cvt_pk_bf16_f32 v12, v2, v3
	v_cvt_pk_bf16_f32 v13, v4, v5
	flat_store_dwordx4 v[166:167], v[10:13]
	s_andn2_b64 vcc, exec, s[36:37]
	s_cbranch_vccnz .LBB0_1793
	s_andn2_b64 vcc, exec, s[0:1]
	s_cbranch_vccnz .LBB0_1792
	s_barrier
	s_branch .LBB0_1792

; template <class Epi, class Sched, bool ALIGN_EPI = false, bool SP2 = false>
; __device__ __forceinline__ void gemm_phase(PG8_LAS unsigned char* lds, const Gemm g, const Sched& S, const Epi& E, int wave_s) {
;     int tid_ = (wave_s << 6) | fresh_lane(); asm volatile("" : "+v"(tid_));
;     const int tid = tid_, wid = __builtin_amdgcn_readfirstlane(tid >> 6), lane = tid & 63, wr = wid >> 2, wc = wid & 3, fr = lane & 15, fq = lane >> 4;
;     const int K = g.K, nt = K / BK;
;     unsigned voffA[2], voffB[2];
; #pragma unroll
;     for (int i = 0; i < 2; ++i) { int R, C; stage_rc(tid * 16 + i * 8192, R, C); const int Rb = Epi::PERM ? ((R & ~31) + perm32(R & 31)) : R;
;         voffA[i] = (unsigned)(R * g.lda + C) * 2u; voffB[i] = (unsigned)(Rb * g.ldb + C) * 2u; }
;     const size_t kstep = (size_t)(BK * 2);
;     const size_t hstepA = (size_t)HALF * g.lda * 2, hstepB = (size_t)HALF * g.ldb * 2;
;     const size_t tstepA = 2 * hstepA, tstepB = 2 * hstepB;
;     const unsigned ldsw = (unsigned)wid * 1024u;
;     const int aoff = lds_byte(wr * 64 + fr, fq * 8), boff = lds_byte(wc * 32 + fr, fq * 8);
;     ...
;     Unit cur, nxt; int ui = 0;
;     if (!S.next(0, cur)) return;
;     f32x4 acc[2][2][4][2];
; #pragma unroll
;     for (int a = 0; a < 2; ++a)
; #pragma unroll
;         for (int b = 0; b < 2; ++b)
; #pragma unroll
;             for (int m = 0; m < 4; ++m)
; #pragma unroll
;                 for (int n = 0; n < 2; ++n) acc[a][b][m][n] = (f32x4){0.f, 0.f, 0.f, 0.f};
;     bf16x8 At[4][2], B0[2][2], B1[2][2];
;     const char* cA = (const char*)g.A + (size_t)cur.pm * tstepA; const char* cB = (const char*)g.Bt + (size_t)cur.pn * tstepB;
;     S.a_ready(cur);
;     if constexpr (SP2) {
;         PG8_STAGE(PG8_SB(0, 0), cB, voffB); PG8_STAGE(PG8_SB(0, 1), cB + hstepB, voffB); PG8_STAGE(PG8_SA(0, 0), cA, voffA); PG8_STAGE(PG8_SA(0, 1), cA + hstepA, voffA);
;         if (wr == 1) PG8_BAR;
;         PG8_WAIT_V(2); PG8_BAR;
;         PG8_STAGE(PG8_SB(1, 0), cB + kstep, voffB); PG8_STAGE(PG8_SA(1, 0), cA + kstep, voffA); PG8_STAGE(PG8_SB(1, 1), cB + hstepB + kstep, voffB);
;         PG8_WAIT_V(6); PG8_BAR;
;     } else {
;         PG8_STAGE(PG8_SB(0, 0), cB, voffB); PG8_STAGE(PG8_SA(0, 0), cA, voffA); PG8_STAGE(PG8_SB(0, 1), cB + hstepB, voffB); PG8_STAGE(PG8_SA(0, 1), cA + hstepA, voffA);
;         if (wr == 1) PG8_BAR;
;         PG8_WAIT_V(4); PG8_BAR;
.LBB0_1853:
	s_load_dwordx2 s[8:9], s[82:83], 0xb8
	v_mov_b32_e32 v0, v1
	s_waitcnt lgkmcnt(0)
	v_readlane_b32 s0, v253, 21
	v_mbcnt_lo_u32_b32 v0, -1, v0
	v_mbcnt_hi_u32_b32 v0, -1, v0
	v_or_b32_e32 v0, s0, v0
	s_and_b64 vcc, exec, s[38:39]
	v_readfirstlane_b32 s0, v0
	v_mov_b32_e32 v0, v1
	s_andn2_b32 s0, s0, 63
	v_mbcnt_lo_u32_b32 v0, -1, v0
	v_mbcnt_hi_u32_b32 v0, -1, v0
	v_or_b32_e32 v18, s0, v0
	s_nop 0
	v_readfirstlane_b32 s10, v18
	s_cbranch_vccnz .LBB0_1877
	v_lshlrev_b32_e32 v0, 4, v18
	v_add_u32_e32 v2, 0x2000, v0
	v_ashrrev_i32_e32 v3, 31, v2
	v_lshrrev_b32_e32 v3, 22, v3
	v_add_u32_e32 v3, v2, v3
	v_ashrrev_i32_e32 v10, 10, v3
	v_mul_i32_i24_e32 v3, 0x400, v10
	v_sub_u32_e32 v2, v2, v3
	v_lshrrev_b32_e32 v3, 4, v2
	v_bitop3_b32 v2, v3, v2, 32 bitop3:0x6c
	v_ashrrev_i32_e32 v3, 31, v2
	v_lshrrev_b32_e32 v3, 26, v3
	v_add_u32_e32 v3, v2, v3
	v_ashrrev_i32_e32 v11, 6, v3
	v_lshlrev_b32_e32 v5, 5, v10
	v_and_b32_e32 v3, 0xc0, v3
	v_and_b32_e32 v12, 32, v5
	v_sub_u32_e32 v2, v2, v3
	v_mov_b32_e32 v5, 1
	v_ashrrev_i16_sdwa v2, v5, sext(v2) dst_sel:DWORD dst_unused:UNUSED_PAD src0_sel:DWORD src1_sel:BYTE_0
	v_bfe_i32 v13, v2, 0, 16
	v_bfe_i32 v2, v18, 27, 1
	v_lshrrev_b32_e32 v2, 22, v2
	v_add_u32_e32 v2, v0, v2
	v_and_b32_e32 v2, 0xfffffc00, v2
	v_sub_u32_e32 v0, v0, v2
	s_add_u32 s2, s8, 0x22d90000
	v_lshrrev_b32_e32 v2, 4, v0
	v_ashrrev_i32_e32 v3, 31, v18
	s_addc_u32 s22, s9, 0
	s_mul_i32 s0, s78, 0x2c00000
	v_bitop3_b32 v0, v2, v0, 32 bitop3:0x6c
	v_lshrrev_b32_e32 v3, 26, v3
	s_add_u32 s0, s8, s0
	v_lshlrev_b32_e32 v4, 3, v10
	v_ashrrev_i32_e32 v2, 31, v0
	v_add_u32_e32 v3, v18, v3
	s_addc_u32 s1, s9, 0
	v_and_b32_e32 v4, 0x7ffff0, v4
	v_lshrrev_b32_e32 v2, 26, v2
	v_ashrrev_i32_e32 v15, 6, v3
	s_add_u32 s24, s0, 0xc790000
	v_add_u32_e32 v4, v11, v4
	s_movk_i32 s0, 32
	v_add_u32_e32 v2, v0, v2
	v_lshlrev_b32_e32 v3, 3, v15
	v_lshl_add_u32 v228, v4, 5, v13
	v_lshl_add_u32 v228, v12, 8, v228
	v_lshlrev_b32_e32 v228, 1, v228
	v_mov_b32_e32 v229, 0
	v_mul_lo_u32 v4, v4, s0
	v_ashrrev_i32_e32 v14, 6, v2
	v_and_b32_e32 v3, 0x7ffff0, v3
	s_addc_u32 s25, s1, 0
	s_ashr_i32 s11, s10, 6
	v_lshl_add_u32 v4, v12, 8, v4
	v_add_u32_e32 v3, v14, v3
	v_and_b32_e32 v2, 0xc0, v2
	s_ashr_i32 s12, s10, 8
	s_lshl_b32 s40, s11, 10
	s_waitcnt vmcnt(0)
	v_add_lshl_u32 v130, v4, v13, 1
	v_mov_b32_e32 v226, v3
	v_mul_lo_u32 v3, v3, s0
	v_lshlrev_b32_e32 v4, 5, v15
	v_sub_u32_e32 v0, v0, v2
	v_readlane_b32 s0, v255, 22
	v_and_b32_e32 v16, 32, v4
	v_ashrrev_i16_sdwa v0, v5, sext(v0) dst_sel:DWORD dst_unused:UNUSED_PAD src0_sel:DWORD src1_sel:BYTE_0
	s_add_u32 s16, s24, s0
	v_readlane_b32 s0, v255, 20
	v_lshl_add_u32 v3, v16, 8, v3
	v_bfe_i32 v17, v0, 0, 16
	s_addc_u32 s17, s25, s0
	s_add_i32 s33, s40, 0
	v_add_lshl_u32 v0, v3, v17, 1
	v_lshl_add_u32 v226, v226, 5, v17
	v_lshl_add_u32 v226, v16, 8, v226
	v_lshlrev_b32_e32 v226, 1, v226
	v_mov_b32_e32 v227, 0
	s_add_i32 m0, s33, 0x10000
	v_mov_b32_e32 v131, v1
	global_load_lds_dwordx4 v0, s[16:17]
	s_add_i32 m0, s33, 0x12000
	s_add_u32 s0, s16, 0x2000
	global_load_lds_dwordx4 v130, s[16:17]
	s_addc_u32 s1, s17, 0
	s_add_i32 m0, s33, 0x14000
	v_lshl_add_u64 v[8:9], s[16:17], 0, v[0:1]
	global_load_lds_dwordx4 v0, s[0:1]
	s_add_i32 m0, s33, 0x16000
	v_lshl_add_u64 v[6:7], s[16:17], 0, v[130:131]
	global_load_lds_dwordx4 v130, s[0:1]
	v_readlane_b32 s0, v255, 19
	s_add_u32 s14, s2, s0
	v_readlane_b32 s0, v255, 16
	s_addc_u32 s15, s22, s0
	s_add_i32 s41, s33, 0x2000
	s_mov_b32 m0, s33
	s_add_u32 s0, s14, 0x2000
	global_load_lds_dwordx4 v226, s[14:15]
	s_mov_b32 m0, s41
	s_addc_u32 s1, s15, 0
	s_add_i32 s42, s33, 0x4000
	global_load_lds_dwordx4 v228, s[14:15]
	s_mov_b32 m0, s42
	s_add_i32 s43, s33, 0x6000
	global_load_lds_dwordx4 v226, s[0:1]
	s_mov_b32 m0, s43
	s_cmp_eq_u32 s12, 1
	global_load_lds_dwordx4 v228, s[0:1]
	v_lshl_add_u64 v[2:3], s[14:15], 0, v[226:227]
	s_cselect_b64 s[0:1], -1, 0
	s_cmp_lg_u32 s12, 1
	v_lshl_add_u64 v[4:5], s[14:15], 0, v[228:229]
	s_cbranch_scc1 .LBB0_1856
	s_barrier
.LBB0_1856:
	s_add_u32 s6, s8, 0x16d90000
	s_addc_u32 s7, s9, 0
	s_mul_i32 s13, s78, 0x48000
	s_add_u32 s8, s8, s13
	s_addc_u32 s9, s9, 0
	v_bfe_u32 v19, v18, 4, 2
	s_add_u32 s44, s8, 0x110000
	v_and_b32_e32 v20, 15, v18
	v_lshlrev_b32_e32 v21, 4, v19
	v_lshlrev_b32_e32 v18, 2, v18
	s_addc_u32 s45, s9, 0
	v_lshl_or_b32 v158, s12, 6, v20
	v_lshl_or_b32 v20, v20, 6, v21
	s_lshl_b32 s8, s12, 13
	v_and_b32_e32 v18, 32, v18
	v_bitop3_b32 v21, v20, s8, v18 bitop3:0xde
	s_lshl_b32 s8, s11, 5
	s_and_b32 s11, s8, 0x60
	s_add_i32 m0, s33, 0x18000
	s_mov_b64 s[100:101], 0x8000
	v_lshl_add_u64 v[8:9], v[8:9], 0, s[100:101]
	s_lshl_b32 s8, s11, 7
	s_waitcnt vmcnt(2)
	s_barrier
	global_load_lds_dwordx4 v[8:9], off
	v_lshl_add_u64 v[6:7], v[6:7], 0, s[100:101]
	s_add_i32 m0, s33, 0x1a000
	s_add_i32 s46, s33, 0x8000
	s_add_i32 s47, s33, 0xa000
	v_bitop3_b32 v159, v20, s8, v18 bitop3:0xde
	global_load_lds_dwordx4 v[6:7], off
	s_mov_b64 s[100:101], 0x8000
	v_lshl_add_u64 v[2:3], v[2:3], 0, s[100:101]
	s_mov_b32 m0, s46
	s_add_u32 s8, s16, 0xa000
	global_load_lds_dwordx4 v[2:3], off
	v_lshl_add_u64 v[2:3], v[4:5], 0, s[100:101]
	s_mov_b32 m0, s47
	s_addc_u32 s9, s17, 0
	global_load_lds_dwordx4 v[2:3], off
	s_add_i32 m0, s33, 0x1c000
	v_lshl_add_u64 v[2:3], s[8:9], 0, v[0:1]
	global_load_lds_dwordx4 v[2:3], off
	v_lshl_add_u64 v[2:3], s[8:9], 0, v[130:131]
	s_add_i32 m0, s33, 0x1e000
	s_movk_i32 s13, 0x1600
	global_load_lds_dwordx4 v[2:3], off
	v_lshrrev_b32_e32 v3, 1, v10
	v_mul_lo_u32 v2, v11, s13
	s_mov_b32 s12, 0x16000
	s_cmpk_lt_u32 s10, 0x100
	v_lshl_or_b32 v160, v19, 2, s11
	v_mad_u64_u32 v[2:3], s[10:11], v3, s12, v[2:3]
	v_or_b32_e32 v2, v2, v12
	v_add_lshl_u32 v2, v2, v13, 1
	v_mov_b32_e32 v3, v1
	s_mov_b64 s[18:19], 0x160080
	s_mov_b64 s[100:101], 0xa000
	v_lshl_add_u64 v[132:133], v[228:229], 0, s[100:101]
	v_lshrrev_b32_e32 v3, 1, v15
	v_mul_lo_u32 v2, v14, s13
	v_mad_u64_u32 v[2:3], s[10:11], v3, s12, v[2:3]
	s_waitcnt vmcnt(6)
	v_or_b32_e32 v2, v2, v16
	v_add_lshl_u32 v2, v2, v17, 1
	v_mov_b32_e32 v3, v1
	v_readlane_b32 s10, v255, 17
	s_cselect_b64 s[8:9], -1, 0
	v_lshl_add_u64 v[134:135], v[226:227], 0, s[100:101]
	s_mov_b32 s48, 0
	v_add_u32_e32 v161, 0, v21
	v_readlane_b32 s26, v255, 21
	s_mov_b32 s51, s10
	s_barrier
	v_readlane_b32 s11, v255, 18
	s_branch .LBB0_1859

; #define PG8_STAGE(bufoff, gbase, voff) do { _Pragma("unroll") for (int _i = 0; _i < 2; ++_i) \
;         __builtin_amdgcn_global_load_lds((const unsigned*)((const char*)(gbase) + (voff)[_i]), (PG8_LAS unsigned*)(lds + (bufoff) + ldsw + _i * 8192), 16, 0, 0); } while (0)
; #define PG8_LDA(dst, b, h) do { _Pragma("unroll") for (int m = 0; m < 4; ++m) _Pragma("unroll") for (int k = 0; k < 2; ++k) dst[m][k] = *(const PG8_LAS bf16x8*)(lds + PG8_SA(b, h) + aoff + m * 2048 + k * 1024); } while (0)
; #define PG8_LDB(dst, b, h) do { _Pragma("unroll") for (int n = 0; n < 2; ++n) _Pragma("unroll") for (int k = 0; k < 2; ++k) dst[n][k] = *(const PG8_LAS bf16x8*)(lds + PG8_SB(b, h) + boff + n * 2048 + k * 1024); } while (0)
; #define PG8_WAIT_V(n) asm volatile("s_waitcnt vmcnt(" #n ")" ::: "memory")
; #define PG8_WAIT_L(n) asm volatile("s_waitcnt lgkmcnt(" #n ")" ::: "memory")
; template <class Epi, class Sched, bool ALIGN_EPI = false, bool SP2 = false>
; __device__ __forceinline__ void gemm_phase(PG8_LAS unsigned char* lds, const Gemm g, const Sched& S, const Epi& E, int wave_s) {
;     ...
;     for (;;) {
;         const bool has_next = S.next(ui + 1, nxt);
;         const char* nA = has_next ? (const char*)g.A + (size_t)nxt.pm * tstepA : cA; const char* nB = has_next ? (const char*)g.Bt + (size_t)nxt.pn * tstepB : cB;
;         for (int t = 0; t < nt; t += 2) {
;             const bool last = (t == nt - 2);
;             const char* a1 = cA + (size_t)(t + 1) * kstep;
;             const char* a2 = last ? nA : cA + (size_t)(t + 2) * kstep; const char* b2 = last ? nB : cB + (size_t)(t + 2) * kstep;
;             const char* a3 = a2 + kstep; const char* b3 = b2 + kstep;
;             if (last && has_next) S.a_ready(nxt);
;             if constexpr (Epi::HAS_MID) { if (t == nt / 2) E.mid(acc, cur, wr, wc, fr, fq); }
;             if constexpr (SP2) {
;             PG8_LDB(B0, 0, 0); PG8_LDB(B1, 0, 1); PG8_SCHED; PG8_LDA(At, 0, 0); PG8_STAGE(PG8_SA(1, 1), a1 + hstepA, voffA);
;             PG8_WAIT_V(8); PG8_WAIT_L(0); PG8_BAR; PG8_MMA(0, 0, At, B0); PG8_MMA(0, 1, At, B1); PG8_BAR; PG8_SCHED;
;             PG8_LDA(At, 0, 1); PG8_STAGE(PG8_SB(0, 0), b2, voffB); PG8_STAGE(PG8_SB(0, 1), b2 + hstepB, voffB); PG8_STAGE(PG8_SA(0, 0), a2, voffA);
;             PG8_WAIT_V(8); PG8_WAIT_L(0); PG8_BAR; PG8_MMA(1, 0, At, B0); PG8_MMA(1, 1, At, B1); PG8_BAR; PG8_SCHED;
.LBB0_1870:
	s_add_u32 s16, s14, 0x10000
	s_addc_u32 s17, s15, 0
	s_add_i32 s34, 0, 0x10000
	s_cmpk_eq_i32 s39, 0x54
	s_cselect_b32 s21, s11, s17
	s_cselect_b32 s20, s10, s16
	s_cselect_b32 s19, s13, s38
	s_cselect_b32 s18, s12, s27
	s_add_i32 s35, 0, 0x14000
	v_add_u32_e32 v148, s34, v159
	v_add_u32_e32 v156, s35, v159
	ds_read_b128 v[136:139], v148
	ds_read_b128 v[140:143], v148 offset:1024
	ds_read_b128 v[144:147], v148 offset:2048
	ds_read_b128 v[148:151], v148 offset:3072
	ds_read_b128 v[152:155], v156
	ds_read_b128 v[162:165], v156 offset:1024
	ds_read_b128 v[166:169], v156 offset:2048
	ds_read_b128 v[176:179], v156 offset:3072
	v_lshl_add_u64 v[156:157], s[14:15], 0, v[134:135]
	s_add_i32 m0, s33, 0xc000
	ds_read_b128 v[180:183], v161
	ds_read_b128 v[184:187], v161 offset:1024
	ds_read_b128 v[188:191], v161 offset:2048
	ds_read_b128 v[192:195], v161 offset:3072
	ds_read_b128 v[196:199], v161 offset:4096
	ds_read_b128 v[208:211], v161 offset:5120
	ds_read_b128 v[212:215], v161 offset:6144
	ds_read_b128 v[216:219], v161 offset:7168
	global_load_lds_dwordx4 v[156:157], off
	v_lshl_add_u64 v[156:157], s[14:15], 0, v[132:133]
	s_add_i32 m0, s33, 0xe000
	s_nop 0
	global_load_lds_dwordx4 v[156:157], off
	s_waitcnt vmcnt(8)
	s_waitcnt lgkmcnt(0)
	s_barrier
	s_setprio 1
	s_waitcnt lgkmcnt(0)
	v_mfma_f32_16x16x32_bf16 v[126:129], v[180:183], v[136:139], v[126:129]
	v_mfma_f32_16x16x32_bf16 v[122:125], v[180:183], v[144:147], v[122:125]
	v_mfma_f32_16x16x32_bf16 v[110:113], v[188:191], v[136:139], v[110:113]
	v_mfma_f32_16x16x32_bf16 v[106:109], v[188:191], v[144:147], v[106:109]
	v_mfma_f32_16x16x32_bf16 v[94:97], v[196:199], v[136:139], v[94:97]
	v_mfma_f32_16x16x32_bf16 v[90:93], v[196:199], v[144:147], v[90:93]
	v_mfma_f32_16x16x32_bf16 v[78:81], v[212:215], v[136:139], v[78:81]
	v_mfma_f32_16x16x32_bf16 v[74:77], v[212:215], v[144:147], v[74:77]
	v_mfma_f32_16x16x32_bf16 v[126:129], v[184:187], v[140:143], v[126:129]
	v_mfma_f32_16x16x32_bf16 v[122:125], v[184:187], v[148:151], v[122:125]
	v_mfma_f32_16x16x32_bf16 v[110:113], v[192:195], v[140:143], v[110:113]
	v_mfma_f32_16x16x32_bf16 v[106:109], v[192:195], v[148:151], v[106:109]
	v_mfma_f32_16x16x32_bf16 v[94:97], v[208:211], v[140:143], v[94:97]
	v_mfma_f32_16x16x32_bf16 v[90:93], v[208:211], v[148:151], v[90:93]
	v_mfma_f32_16x16x32_bf16 v[78:81], v[216:219], v[140:143], v[78:81]
	v_mfma_f32_16x16x32_bf16 v[74:77], v[216:219], v[148:151], v[74:77]
	s_setprio 0
	s_setprio 1
	v_mfma_f32_16x16x32_bf16 v[118:121], v[180:183], v[152:155], v[118:121]
	v_mfma_f32_16x16x32_bf16 v[114:117], v[180:183], v[166:169], v[114:117]
	v_mfma_f32_16x16x32_bf16 v[102:105], v[188:191], v[152:155], v[102:105]
	v_mfma_f32_16x16x32_bf16 v[98:101], v[188:191], v[166:169], v[98:101]
	v_mfma_f32_16x16x32_bf16 v[86:89], v[196:199], v[152:155], v[86:89]
	v_mfma_f32_16x16x32_bf16 v[82:85], v[196:199], v[166:169], v[82:85]
	v_mfma_f32_16x16x32_bf16 v[70:73], v[212:215], v[152:155], v[70:73]
	v_mfma_f32_16x16x32_bf16 v[66:69], v[212:215], v[166:169], v[66:69]
	v_mfma_f32_16x16x32_bf16 v[118:121], v[184:187], v[162:165], v[118:121]
	v_mfma_f32_16x16x32_bf16 v[114:117], v[184:187], v[176:179], v[114:117]
	v_mfma_f32_16x16x32_bf16 v[102:105], v[192:195], v[162:165], v[102:105]
	v_mfma_f32_16x16x32_bf16 v[98:101], v[192:195], v[176:179], v[98:101]
	v_mfma_f32_16x16x32_bf16 v[86:89], v[208:211], v[162:165], v[86:89]
	v_mfma_f32_16x16x32_bf16 v[82:85], v[208:211], v[176:179], v[82:85]
	v_mfma_f32_16x16x32_bf16 v[70:73], v[216:219], v[162:165], v[70:73]
	v_mfma_f32_16x16x32_bf16 v[66:69], v[216:219], v[176:179], v[66:69]
	s_setprio 0
	s_barrier
	s_add_i32 s14, s34, s40
	v_lshl_add_u64 v[156:157], s[18:19], 0, v[0:1]
	s_mov_b32 m0, s14
	ds_read_b128 v[180:183], v161 offset:16384
	ds_read_b128 v[184:187], v161 offset:17408
	ds_read_b128 v[188:191], v161 offset:18432
	ds_read_b128 v[192:195], v161 offset:19456
	ds_read_b128 v[196:199], v161 offset:20480
	ds_read_b128 v[208:211], v161 offset:21504
	ds_read_b128 v[212:215], v161 offset:22528
	ds_read_b128 v[216:219], v161 offset:23552
	global_load_lds_dwordx4 v[156:157], off
	s_add_i32 m0, s14, 0x2000
	s_add_u32 s14, s18, 0x2000
	v_lshl_add_u64 v[170:171], s[18:19], 0, v[130:131]
	s_addc_u32 s15, s19, 0
	s_add_i32 s34, s35, s40
	global_load_lds_dwordx4 v[170:171], off
	v_lshl_add_u64 v[200:201], s[14:15], 0, v[0:1]
	s_mov_b32 m0, s34
	v_lshl_add_u64 v[220:221], s[20:21], 0, v[228:229]
	global_load_lds_dwordx4 v[200:201], off
	v_lshl_add_u64 v[200:201], s[14:15], 0, v[130:131]
	s_add_i32 m0, s34, 0x2000
	s_nop 0
	global_load_lds_dwordx4 v[200:201], off
	v_lshl_add_u64 v[200:201], s[20:21], 0, v[226:227]
	s_mov_b32 m0, s33
	s_nop 0
	global_load_lds_dwordx4 v[200:201], off
	s_mov_b32 m0, s41
	s_nop 0
	global_load_lds_dwordx4 v[220:221], off
	s_waitcnt vmcnt(8)
	s_waitcnt lgkmcnt(0)
	s_barrier
; #define PG8_STAGE(bufoff, gbase, voff) do { _Pragma("unroll") for (int _i = 0; _i < 2; ++_i) \
;         __builtin_amdgcn_global_load_lds((const unsigned*)((const char*)(gbase) + (voff)[_i]), (PG8_LAS unsigned*)(lds + (bufoff) + ldsw + _i * 8192), 16, 0, 0); } while (0)
; #define PG8_LDA(dst, b, h) do { _Pragma("unroll") for (int m = 0; m < 4; ++m) _Pragma("unroll") for (int k = 0; k < 2; ++k) dst[m][k] = *(const PG8_LAS bf16x8*)(lds + PG8_SA(b, h) + aoff + m * 2048 + k * 1024); } while (0)
; #define PG8_LDB(dst, b, h) do { _Pragma("unroll") for (int n = 0; n < 2; ++n) _Pragma("unroll") for (int k = 0; k < 2; ++k) dst[n][k] = *(const PG8_LAS bf16x8*)(lds + PG8_SB(b, h) + boff + n * 2048 + k * 1024); } while (0)
; #define PG8_MMA(ai, bj, At, Bt) do { __builtin_amdgcn_s_setprio(1); _Pragma("unroll") for (int m = 0; m < 4; ++m) _Pragma("unroll") for (int n = 0; n < 2; ++n) _Pragma("unroll") for (int k = 0; k < 2; ++k) \
;         acc[ai][bj][m][n] = __builtin_amdgcn_mfma_f32_16x16x32_bf16(Bt[n][k], At[m][k], acc[ai][bj][m][n], 0, 0, 0); __builtin_amdgcn_s_setprio(0); } while (0)
; #define PG8_WAIT_V(n) asm volatile("s_waitcnt vmcnt(" #n ")" ::: "memory")
; #define PG8_WAIT_L(n) asm volatile("s_waitcnt lgkmcnt(" #n ")" ::: "memory")
; #define PG8_BAR __builtin_amdgcn_s_barrier()
; #define PG8_SCHED __builtin_amdgcn_sched_barrier(0)
; template <class Epi, class Sched, bool ALIGN_EPI = false, bool SP2 = false>
; __device__ __forceinline__ void gemm_phase(PG8_LAS unsigned char* lds, const Gemm g, const Sched& S, const Epi& E, int wave_s) {
;     ...
;             PG8_WAIT_V(8); PG8_WAIT_L(0); PG8_BAR; PG8_MMA(0, 0, At, B0); PG8_MMA(0, 1, At, B1); PG8_BAR; PG8_SCHED;
;             PG8_LDA(At, 0, 1); PG8_STAGE(PG8_SB(0, 0), b2, voffB); PG8_STAGE(PG8_SB(0, 1), b2 + hstepB, voffB); PG8_STAGE(PG8_SA(0, 0), a2, voffA);
;             PG8_WAIT_V(8); PG8_WAIT_L(0); PG8_BAR; PG8_MMA(1, 0, At, B0); PG8_MMA(1, 1, At, B1); PG8_BAR; PG8_SCHED;
;             PG8_LDB(B0, 1, 0); PG8_LDB(B1, 1, 1); PG8_SCHED; PG8_LDA(At, 1, 0); PG8_STAGE(PG8_SA(0, 1), a2 + hstepA, voffA);
;             PG8_WAIT_V(8); PG8_WAIT_L(0); PG8_BAR; PG8_MMA(0, 0, At, B0); PG8_MMA(0, 1, At, B1); PG8_BAR; PG8_SCHED;
	s_setprio 1
	s_waitcnt lgkmcnt(0)
	v_mfma_f32_16x16x32_bf16 v[62:65], v[180:183], v[136:139], v[62:65]
	v_mfma_f32_16x16x32_bf16 v[58:61], v[180:183], v[144:147], v[58:61]
	v_mfma_f32_16x16x32_bf16 v[46:49], v[188:191], v[136:139], v[46:49]
	v_mfma_f32_16x16x32_bf16 v[42:45], v[188:191], v[144:147], v[42:45]
	v_mfma_f32_16x16x32_bf16 v[30:33], v[196:199], v[136:139], v[30:33]
	v_mfma_f32_16x16x32_bf16 v[26:29], v[196:199], v[144:147], v[26:29]
	v_mfma_f32_16x16x32_bf16 v[14:17], v[212:215], v[136:139], v[14:17]
	v_mfma_f32_16x16x32_bf16 v[10:13], v[212:215], v[144:147], v[10:13]
	v_mfma_f32_16x16x32_bf16 v[62:65], v[184:187], v[140:143], v[62:65]
	v_mfma_f32_16x16x32_bf16 v[58:61], v[184:187], v[148:151], v[58:61]
	v_mfma_f32_16x16x32_bf16 v[46:49], v[192:195], v[140:143], v[46:49]
	v_mfma_f32_16x16x32_bf16 v[42:45], v[192:195], v[148:151], v[42:45]
	v_mfma_f32_16x16x32_bf16 v[30:33], v[208:211], v[140:143], v[30:33]
	v_mfma_f32_16x16x32_bf16 v[26:29], v[208:211], v[148:151], v[26:29]
	v_mfma_f32_16x16x32_bf16 v[14:17], v[216:219], v[140:143], v[14:17]
	v_mfma_f32_16x16x32_bf16 v[10:13], v[216:219], v[148:151], v[10:13]
	s_setprio 0
	s_setprio 1
	v_mfma_f32_16x16x32_bf16 v[54:57], v[180:183], v[152:155], v[54:57]
	v_mfma_f32_16x16x32_bf16 v[50:53], v[180:183], v[166:169], v[50:53]
	v_mfma_f32_16x16x32_bf16 v[38:41], v[188:191], v[152:155], v[38:41]
	v_mfma_f32_16x16x32_bf16 v[34:37], v[188:191], v[166:169], v[34:37]
	v_mfma_f32_16x16x32_bf16 v[22:25], v[196:199], v[152:155], v[22:25]
	v_mfma_f32_16x16x32_bf16 v[18:21], v[196:199], v[166:169], v[18:21]
	v_mfma_f32_16x16x32_bf16 v[6:9], v[212:215], v[152:155], v[6:9]
	v_mfma_f32_16x16x32_bf16 v[2:5], v[212:215], v[166:169], v[2:5]
	v_mfma_f32_16x16x32_bf16 v[54:57], v[184:187], v[162:165], v[54:57]
	v_mfma_f32_16x16x32_bf16 v[50:53], v[184:187], v[176:179], v[50:53]
	v_mfma_f32_16x16x32_bf16 v[38:41], v[192:195], v[162:165], v[38:41]
	v_mfma_f32_16x16x32_bf16 v[34:37], v[192:195], v[176:179], v[34:37]
	v_mfma_f32_16x16x32_bf16 v[22:25], v[208:211], v[162:165], v[22:25]
	v_mfma_f32_16x16x32_bf16 v[18:21], v[208:211], v[176:179], v[18:21]
	v_mfma_f32_16x16x32_bf16 v[6:9], v[216:219], v[162:165], v[6:9]
	v_mfma_f32_16x16x32_bf16 v[2:5], v[216:219], v[176:179], v[2:5]
	s_setprio 0
	s_barrier
	s_add_i32 s34, 0, 0x18000
	s_add_i32 s35, 0, 0x1c000
	v_add_u32_e32 v148, s34, v159
	v_add_u32_e32 v176, s35, v159
	ds_read_b128 v[136:139], v148
	ds_read_b128 v[140:143], v148 offset:1024
	ds_read_b128 v[144:147], v148 offset:2048
	ds_read_b128 v[148:151], v148 offset:3072
	ds_read_b128 v[152:155], v176
	ds_read_b128 v[162:165], v176 offset:1024
	ds_read_b128 v[166:169], v176 offset:2048
	ds_read_b128 v[176:179], v176 offset:3072
	s_add_u32 s14, s20, 0x2000
	s_addc_u32 s15, s21, 0
	s_mov_b32 m0, s42
	v_lshl_add_u64 v[222:223], s[14:15], 0, v[226:227]
	ds_read_b128 v[180:183], v161 offset:32768
	ds_read_b128 v[184:187], v161 offset:33792
	ds_read_b128 v[188:191], v161 offset:34816
	ds_read_b128 v[192:195], v161 offset:35840
	ds_read_b128 v[196:199], v161 offset:36864
	ds_read_b128 v[208:211], v161 offset:37888
	ds_read_b128 v[212:215], v161 offset:38912
	ds_read_b128 v[216:219], v161 offset:39936
	global_load_lds_dwordx4 v[222:223], off
	v_lshl_add_u64 v[222:223], s[14:15], 0, v[228:229]
	s_mov_b32 m0, s43
	s_nop 0
	global_load_lds_dwordx4 v[222:223], off
	s_waitcnt vmcnt(8)
	s_waitcnt lgkmcnt(0)
	s_barrier
	s_setprio 1
	s_waitcnt lgkmcnt(0)
	v_mfma_f32_16x16x32_bf16 v[126:129], v[180:183], v[136:139], v[126:129]
	v_mfma_f32_16x16x32_bf16 v[122:125], v[180:183], v[144:147], v[122:125]
	v_mfma_f32_16x16x32_bf16 v[110:113], v[188:191], v[136:139], v[110:113]
	v_mfma_f32_16x16x32_bf16 v[106:109], v[188:191], v[144:147], v[106:109]
	v_mfma_f32_16x16x32_bf16 v[94:97], v[196:199], v[136:139], v[94:97]
	v_mfma_f32_16x16x32_bf16 v[90:93], v[196:199], v[144:147], v[90:93]
	v_mfma_f32_16x16x32_bf16 v[78:81], v[212:215], v[136:139], v[78:81]
	v_mfma_f32_16x16x32_bf16 v[74:77], v[212:215], v[144:147], v[74:77]
	v_mfma_f32_16x16x32_bf16 v[126:129], v[184:187], v[140:143], v[126:129]
	v_mfma_f32_16x16x32_bf16 v[122:125], v[184:187], v[148:151], v[122:125]
	v_mfma_f32_16x16x32_bf16 v[110:113], v[192:195], v[140:143], v[110:113]
	v_mfma_f32_16x16x32_bf16 v[106:109], v[192:195], v[148:151], v[106:109]
	v_mfma_f32_16x16x32_bf16 v[94:97], v[208:211], v[140:143], v[94:97]
	v_mfma_f32_16x16x32_bf16 v[90:93], v[208:211], v[148:151], v[90:93]
	v_mfma_f32_16x16x32_bf16 v[78:81], v[216:219], v[140:143], v[78:81]
	v_mfma_f32_16x16x32_bf16 v[74:77], v[216:219], v[148:151], v[74:77]
	s_setprio 0
	s_setprio 1
	v_mfma_f32_16x16x32_bf16 v[118:121], v[180:183], v[152:155], v[118:121]
	v_mfma_f32_16x16x32_bf16 v[114:117], v[180:183], v[166:169], v[114:117]
	v_mfma_f32_16x16x32_bf16 v[102:105], v[188:191], v[152:155], v[102:105]
	v_mfma_f32_16x16x32_bf16 v[98:101], v[188:191], v[166:169], v[98:101]
	v_mfma_f32_16x16x32_bf16 v[86:89], v[196:199], v[152:155], v[86:89]
	v_mfma_f32_16x16x32_bf16 v[82:85], v[196:199], v[166:169], v[82:85]
	v_mfma_f32_16x16x32_bf16 v[70:73], v[212:215], v[152:155], v[70:73]
	v_mfma_f32_16x16x32_bf16 v[66:69], v[212:215], v[166:169], v[66:69]
	v_mfma_f32_16x16x32_bf16 v[118:121], v[184:187], v[162:165], v[118:121]
	v_mfma_f32_16x16x32_bf16 v[114:117], v[184:187], v[176:179], v[114:117]
	v_mfma_f32_16x16x32_bf16 v[102:105], v[192:195], v[162:165], v[102:105]
	v_mfma_f32_16x16x32_bf16 v[98:101], v[192:195], v[176:179], v[98:101]
	v_mfma_f32_16x16x32_bf16 v[86:89], v[208:211], v[162:165], v[86:89]
	v_mfma_f32_16x16x32_bf16 v[82:85], v[208:211], v[176:179], v[82:85]
	v_mfma_f32_16x16x32_bf16 v[70:73], v[216:219], v[162:165], v[70:73]
	v_mfma_f32_16x16x32_bf16 v[66:69], v[216:219], v[176:179], v[66:69]
	s_setprio 0
	s_barrier
; #define PG8_STAGE(bufoff, gbase, voff) do { _Pragma("unroll") for (int _i = 0; _i < 2; ++_i) \
;         __builtin_amdgcn_global_load_lds((const unsigned*)((const char*)(gbase) + (voff)[_i]), (PG8_LAS unsigned*)(lds + (bufoff) + ldsw + _i * 8192), 16, 0, 0); } while (0)
; #define PG8_LDA(dst, b, h) do { _Pragma("unroll") for (int m = 0; m < 4; ++m) _Pragma("unroll") for (int k = 0; k < 2; ++k) dst[m][k] = *(const PG8_LAS bf16x8*)(lds + PG8_SA(b, h) + aoff + m * 2048 + k * 1024); } while (0)
; #define PG8_WAIT_V(n) asm volatile("s_waitcnt vmcnt(" #n ")" ::: "memory")
; #define PG8_BAR __builtin_amdgcn_s_barrier()
; template <class Epi, class Sched, bool ALIGN_EPI = false, bool SP2 = false>
; __device__ __forceinline__ void gemm_phase(PG8_LAS unsigned char* lds, const Gemm g, const Sched& S, const Epi& E, int wave_s) {
;     ...
;         for (int t = 0; t < nt; t += 2) {
;             const bool last = (t == nt - 2);
;             const char* a1 = cA + (size_t)(t + 1) * kstep;
;             const char* a2 = last ? nA : cA + (size_t)(t + 2) * kstep; const char* b2 = last ? nB : cB + (size_t)(t + 2) * kstep;
;             const char* a3 = a2 + kstep; const char* b3 = b2 + kstep;
;             if (last && has_next) S.a_ready(nxt);
;             if constexpr (Epi::HAS_MID) { if (t == nt / 2) E.mid(acc, cur, wr, wc, fr, fq); }
;             if constexpr (SP2) {
;             PG8_LDB(B0, 0, 0); PG8_LDB(B1, 0, 1); PG8_SCHED; PG8_LDA(At, 0, 0); PG8_STAGE(PG8_SA(1, 1), a1 + hstepA, voffA);
;             PG8_WAIT_V(8); PG8_WAIT_L(0); PG8_BAR; PG8_MMA(0, 0, At, B0); PG8_MMA(0, 1, At, B1); PG8_BAR; PG8_SCHED;
;             PG8_LDA(At, 0, 1); PG8_STAGE(PG8_SB(0, 0), b2, voffB); PG8_STAGE(PG8_SB(0, 1), b2 + hstepB, voffB); PG8_STAGE(PG8_SA(0, 0), a2, voffA);
;             PG8_WAIT_V(8); PG8_WAIT_L(0); PG8_BAR; PG8_MMA(1, 0, At, B0); PG8_MMA(1, 1, At, B1); PG8_BAR; PG8_SCHED;
;             PG8_LDB(B0, 1, 0); PG8_LDB(B1, 1, 1); PG8_SCHED; PG8_LDA(At, 1, 0); PG8_STAGE(PG8_SA(0, 1), a2 + hstepA, voffA);
;             PG8_WAIT_V(8); PG8_WAIT_L(0); PG8_BAR; PG8_MMA(0, 0, At, B0); PG8_MMA(0, 1, At, B1); PG8_BAR; PG8_SCHED;
;             PG8_LDA(At, 1, 1); PG8_STAGE(PG8_SB(1, 0), b3, voffB); PG8_STAGE(PG8_SB(1, 1), b3 + hstepB, voffB); PG8_STAGE(PG8_SA(1, 0), a3, voffA);
;             PG8_WAIT_V(8); PG8_WAIT_L(0); PG8_BAR; PG8_MMA(1, 0, At, B0); PG8_MMA(1, 1, At, B1); PG8_BAR; PG8_SCHED;
	s_add_i32 s14, s34, s40
	s_mov_b64 s[100:101], 0x8000
	v_lshl_add_u64 v[156:157], v[156:157], 0, s[100:101]
	s_mov_b32 m0, s14
	ds_read_b128 v[180:183], v161 offset:49152
	ds_read_b128 v[184:187], v161 offset:50176
	ds_read_b128 v[188:191], v161 offset:51200
	ds_read_b128 v[192:195], v161 offset:52224
	ds_read_b128 v[196:199], v161 offset:53248
	ds_read_b128 v[208:211], v161 offset:54272
	ds_read_b128 v[212:215], v161 offset:55296
	ds_read_b128 v[216:219], v161 offset:56320
	global_load_lds_dwordx4 v[156:157], off
	s_add_i32 m0, s14, 0x2000
	s_add_u32 s14, s18, 0xa000
	v_lshl_add_u64 v[156:157], v[170:171], 0, s[100:101]
	s_addc_u32 s15, s19, 0
	s_add_i32 s18, s35, s40
	global_load_lds_dwordx4 v[156:157], off
	v_lshl_add_u64 v[156:157], s[14:15], 0, v[0:1]
	s_mov_b32 m0, s18
	s_nop 0
	global_load_lds_dwordx4 v[156:157], off
	v_lshl_add_u64 v[156:157], s[14:15], 0, v[130:131]
	s_add_i32 m0, s18, 0x2000
	s_nop 0
	global_load_lds_dwordx4 v[156:157], off
	s_mov_b64 s[100:101], 0x8000
	v_lshl_add_u64 v[156:157], v[200:201], 0, s[100:101]
	s_mov_b32 m0, s46
	s_nop 0
	global_load_lds_dwordx4 v[156:157], off
	v_lshl_add_u64 v[156:157], v[220:221], 0, s[100:101]
	s_mov_b32 m0, s47
	s_nop 0
	global_load_lds_dwordx4 v[156:157], off
	s_waitcnt vmcnt(8)
	s_waitcnt lgkmcnt(0)
	s_barrier
	s_setprio 1
	s_waitcnt lgkmcnt(0)
	v_mfma_f32_16x16x32_bf16 v[62:65], v[180:183], v[136:139], v[62:65]
	v_mfma_f32_16x16x32_bf16 v[58:61], v[180:183], v[144:147], v[58:61]
	v_mfma_f32_16x16x32_bf16 v[46:49], v[188:191], v[136:139], v[46:49]
	v_mfma_f32_16x16x32_bf16 v[42:45], v[188:191], v[144:147], v[42:45]
	v_mfma_f32_16x16x32_bf16 v[30:33], v[196:199], v[136:139], v[30:33]
	v_mfma_f32_16x16x32_bf16 v[26:29], v[196:199], v[144:147], v[26:29]
	v_mfma_f32_16x16x32_bf16 v[14:17], v[212:215], v[136:139], v[14:17]
	v_mfma_f32_16x16x32_bf16 v[10:13], v[212:215], v[144:147], v[10:13]
	v_mfma_f32_16x16x32_bf16 v[62:65], v[184:187], v[140:143], v[62:65]
	v_mfma_f32_16x16x32_bf16 v[58:61], v[184:187], v[148:151], v[58:61]
	v_mfma_f32_16x16x32_bf16 v[46:49], v[192:195], v[140:143], v[46:49]
	v_mfma_f32_16x16x32_bf16 v[42:45], v[192:195], v[148:151], v[42:45]
	v_mfma_f32_16x16x32_bf16 v[30:33], v[208:211], v[140:143], v[30:33]
	v_mfma_f32_16x16x32_bf16 v[26:29], v[208:211], v[148:151], v[26:29]
	v_mfma_f32_16x16x32_bf16 v[14:17], v[216:219], v[140:143], v[14:17]
	v_mfma_f32_16x16x32_bf16 v[10:13], v[216:219], v[148:151], v[10:13]
	s_setprio 0
	s_setprio 1
	v_mfma_f32_16x16x32_bf16 v[54:57], v[180:183], v[152:155], v[54:57]
	v_mfma_f32_16x16x32_bf16 v[50:53], v[180:183], v[166:169], v[50:53]
	v_mfma_f32_16x16x32_bf16 v[38:41], v[188:191], v[152:155], v[38:41]
	v_mfma_f32_16x16x32_bf16 v[34:37], v[188:191], v[166:169], v[34:37]
	v_mfma_f32_16x16x32_bf16 v[22:25], v[196:199], v[152:155], v[22:25]
	v_mfma_f32_16x16x32_bf16 v[18:21], v[196:199], v[166:169], v[18:21]
	v_mfma_f32_16x16x32_bf16 v[6:9], v[212:215], v[152:155], v[6:9]
	v_mfma_f32_16x16x32_bf16 v[2:5], v[212:215], v[166:169], v[2:5]
	v_mfma_f32_16x16x32_bf16 v[54:57], v[184:187], v[162:165], v[54:57]
	v_mfma_f32_16x16x32_bf16 v[50:53], v[184:187], v[176:179], v[50:53]
	v_mfma_f32_16x16x32_bf16 v[38:41], v[192:195], v[162:165], v[38:41]
	v_mfma_f32_16x16x32_bf16 v[34:37], v[192:195], v[176:179], v[34:37]
	v_mfma_f32_16x16x32_bf16 v[22:25], v[208:211], v[162:165], v[22:25]
	v_mfma_f32_16x16x32_bf16 v[18:21], v[208:211], v[176:179], v[18:21]
	v_mfma_f32_16x16x32_bf16 v[6:9], v[216:219], v[162:165], v[6:9]
	v_mfma_f32_16x16x32_bf16 v[2:5], v[216:219], v[176:179], v[2:5]
	s_setprio 0
	s_barrier
	s_add_i32 s39, s39, 2
	s_add_u32 s27, s27, 0x10000
	s_addc_u32 s38, s38, 0
	s_cmpk_gt_u32 s39, 0x55
	s_mov_b64 s[14:15], s[16:17]
	s_cbranch_scc0 .LBB0_1870
	s_and_b64 vcc, exec, s[8:9]
	s_cbranch_vccz .LBB0_1873
	s_barrier
